# c41 + write-through (sc1) also on the attention output stores (2-byte) and the DIFF stash stores
# baseline (speedup 1.0000x reference)
.LBB0_131:
	s_or_b64 exec, exec, s[48:49]
	v_cvt_f32_f64_e32 v9, v[26:27]
	v_cvt_f32_f64_e32 v26, v[28:29]
	global_store_dword v[0:1], v26, off sc1
	v_add_co_u32_e32 v26, vcc, 0x100000, v0
	v_add_u32_e32 v8, s18, v8
	s_nop 0
	v_addc_co_u32_e32 v27, vcc, 0, v1, vcc
	v_cmp_lt_i32_e32 vcc, s1, v8
	s_or_b64 s[36:37], vcc, s[36:37]
	v_lshl_add_u64 v[0:1], v[0:1], 0, s[34:35]
	global_store_dword v[26:27], v9, off sc1
	s_andn2_b64 exec, exec, s[36:37]
	s_cbranch_execz .LBB0_135

.LBB0_257:
	v_cndmask_b32_e64 v112, 0, 1, s[10:11]
	v_cmp_ne_u32_e64 s[16:17], 1, v112
	s_andn2_b64 vcc, exec, s[10:11]
	v_cmp_gt_u32_e64 s[10:11], 16, v163
	s_cbranch_vccnz .LBB0_261
	ds_bpermute_b32 v112, v158, v164
	s_waitcnt lgkmcnt(0)
	v_add_f32_e32 v112, v164, v112
	ds_bpermute_b32 v113, v159, v112
	s_and_saveexec_b64 s[18:19], s[10:11]
	s_cbranch_execz .LBB0_260
	s_waitcnt lgkmcnt(0)
	v_add_f32_e32 v114, v112, v113
	s_cmp_eq_u32 s36, 0
	v_lshlrev_b64 v[112:113], 6, v[144:145]
	s_cselect_b32 s76, 0, 16
	s_mov_b32 s77, s39
	v_lshl_add_u64 v[112:113], s[52:53], 0, v[112:113]
	v_lshl_add_u64 v[112:113], v[112:113], 0, s[76:77]
	s_lshl_b32 s76, s25, 2
	v_lshl_add_u64 v[112:113], v[112:113], 0, s[76:77]
	global_store_dword v[112:113], v114, off sc1

.LBB0_261:
	s_cmp_gt_i32 s36, 0
	s_cselect_b64 s[76:77], -1, 0
	s_cmp_lt_i32 s36, 1
	s_cbranch_scc1 .LBB0_265
	ds_bpermute_b32 v112, v158, v165
	s_waitcnt lgkmcnt(0)
	v_add_f32_e32 v112, v165, v112
	ds_bpermute_b32 v113, v159, v112
	s_and_saveexec_b64 s[18:19], s[10:11]
	s_cbranch_execz .LBB0_264
	s_waitcnt lgkmcnt(0)
	v_add_f32_e32 v114, v112, v113
	s_cmp_eq_u32 s36, 1
	v_lshlrev_b64 v[112:113], 6, v[144:145]
	s_cselect_b32 s78, 32, 48
	s_mov_b32 s79, s39
	v_lshl_add_u64 v[112:113], s[52:53], 0, v[112:113]
	v_lshl_add_u64 v[112:113], v[112:113], 0, s[78:79]
	s_lshl_b32 s78, s25, 2
	v_lshl_add_u64 v[112:113], v[112:113], 0, s[78:79]
	global_store_dword v[112:113], v114, off sc1

.LBB0_315:
	ds_bpermute_b32 v96, v158, v124
	s_waitcnt lgkmcnt(0)
	v_add_f32_e32 v96, v124, v96
	ds_bpermute_b32 v97, v159, v96
	s_and_saveexec_b64 s[18:19], s[10:11]
	s_cbranch_execz .LBB0_317
	s_waitcnt lgkmcnt(0)
	v_add_f32_e32 v98, v96, v97
	s_cmp_eq_u32 s36, 0
	v_lshlrev_b64 v[96:97], 6, v[112:113]
	s_cselect_b32 s78, 0, 16
	s_mov_b32 s79, s39
	v_lshl_add_u64 v[96:97], s[52:53], 0, v[96:97]
	v_lshl_add_u64 v[96:97], v[96:97], 0, s[78:79]
	s_lshl_b32 s78, s25, 2
	v_lshl_add_u64 v[96:97], v[96:97], 0, s[78:79]
	global_store_dword v[96:97], v98, off sc1

.LBB0_318:
	ds_bpermute_b32 v96, v158, v125
	s_waitcnt lgkmcnt(0)
	v_add_f32_e32 v96, v125, v96
	ds_bpermute_b32 v97, v159, v96
	s_and_saveexec_b64 s[76:77], s[10:11]
	s_cbranch_execz .LBB0_320
	s_waitcnt lgkmcnt(0)
	v_add_f32_e32 v98, v96, v97
	s_cmp_eq_u32 s36, 1
	v_lshlrev_b64 v[96:97], 6, v[112:113]
	s_cselect_b32 s78, 32, 48
	s_mov_b32 s79, s39
	v_lshl_add_u64 v[96:97], s[52:53], 0, v[96:97]
	v_lshl_add_u64 v[96:97], v[96:97], 0, s[78:79]
	s_lshl_b32 s78, s25, 2
	v_lshl_add_u64 v[96:97], v[96:97], 0, s[78:79]
	global_store_dword v[96:97], v98, off sc1

.LBB0_371:
	ds_bpermute_b32 v80, v158, v108
	s_waitcnt lgkmcnt(0)
	v_add_f32_e32 v80, v108, v80
	ds_bpermute_b32 v81, v159, v80
	s_and_saveexec_b64 s[76:77], s[10:11]
	s_cbranch_execz .LBB0_373
	s_waitcnt lgkmcnt(0)
	v_add_f32_e32 v82, v80, v81
	s_cmp_eq_u32 s36, 0
	v_lshlrev_b64 v[80:81], 6, v[96:97]
	s_cselect_b32 s78, 0, 16
	s_mov_b32 s79, s39
	v_lshl_add_u64 v[80:81], s[52:53], 0, v[80:81]
	v_lshl_add_u64 v[80:81], v[80:81], 0, s[78:79]
	s_lshl_b32 s78, s25, 2
	v_lshl_add_u64 v[80:81], v[80:81], 0, s[78:79]
	global_store_dword v[80:81], v82, off sc1

.LBB0_374:
	ds_bpermute_b32 v80, v158, v109
	s_waitcnt lgkmcnt(0)
	v_add_f32_e32 v80, v109, v80
	ds_bpermute_b32 v81, v159, v80
	s_and_saveexec_b64 s[76:77], s[10:11]
	s_cbranch_execz .LBB0_376
	s_waitcnt lgkmcnt(0)
	v_add_f32_e32 v82, v80, v81
	s_cmp_eq_u32 s36, 1
	v_lshlrev_b64 v[80:81], 6, v[96:97]
	s_cselect_b32 s78, 32, 48
	s_mov_b32 s79, s39
	v_lshl_add_u64 v[80:81], s[52:53], 0, v[80:81]
	v_lshl_add_u64 v[80:81], v[80:81], 0, s[78:79]
	s_lshl_b32 s78, s25, 2
	v_lshl_add_u64 v[80:81], v[80:81], 0, s[78:79]
	global_store_dword v[80:81], v82, off sc1

.LBB0_427:
	ds_bpermute_b32 v64, v158, v92
	s_waitcnt lgkmcnt(0)
	v_add_f32_e32 v64, v92, v64
	ds_bpermute_b32 v65, v159, v64
	s_and_saveexec_b64 s[76:77], s[10:11]
	s_cbranch_execz .LBB0_429
	s_waitcnt lgkmcnt(0)
	v_add_f32_e32 v66, v64, v65
	s_cmp_eq_u32 s36, 0
	v_lshlrev_b64 v[64:65], 6, v[80:81]
	s_cselect_b32 s78, 0, 16
	s_mov_b32 s79, s39
	v_lshl_add_u64 v[64:65], s[52:53], 0, v[64:65]
	v_lshl_add_u64 v[64:65], v[64:65], 0, s[78:79]
	s_lshl_b32 s78, s25, 2
	v_lshl_add_u64 v[64:65], v[64:65], 0, s[78:79]
	global_store_dword v[64:65], v66, off sc1

.LBB0_430:
	ds_bpermute_b32 v64, v158, v93
	s_waitcnt lgkmcnt(0)
	v_add_f32_e32 v64, v93, v64
	ds_bpermute_b32 v65, v159, v64
	s_and_saveexec_b64 s[76:77], s[10:11]
	s_cbranch_execz .LBB0_432
	s_waitcnt lgkmcnt(0)
	v_add_f32_e32 v66, v64, v65
	s_cmp_eq_u32 s36, 1
	v_lshlrev_b64 v[64:65], 6, v[80:81]
	s_cselect_b32 s78, 32, 48
	s_mov_b32 s79, s39
	v_lshl_add_u64 v[64:65], s[52:53], 0, v[64:65]
	v_lshl_add_u64 v[64:65], v[64:65], 0, s[78:79]
	s_lshl_b32 s78, s25, 2
	v_lshl_add_u64 v[64:65], v[64:65], 0, s[78:79]
	global_store_dword v[64:65], v66, off sc1

.LBB0_483:
	ds_bpermute_b32 v48, v158, v76
	s_waitcnt lgkmcnt(0)
	v_add_f32_e32 v48, v76, v48
	ds_bpermute_b32 v49, v159, v48
	s_and_saveexec_b64 s[76:77], s[10:11]
	s_cbranch_execz .LBB0_485
	s_waitcnt lgkmcnt(0)
	v_add_f32_e32 v50, v48, v49
	s_cmp_eq_u32 s36, 0
	v_lshlrev_b64 v[48:49], 6, v[64:65]
	s_cselect_b32 s78, 0, 16
	s_mov_b32 s79, s39
	v_lshl_add_u64 v[48:49], s[52:53], 0, v[48:49]
	v_lshl_add_u64 v[48:49], v[48:49], 0, s[78:79]
	s_lshl_b32 s78, s25, 2
	v_lshl_add_u64 v[48:49], v[48:49], 0, s[78:79]
	global_store_dword v[48:49], v50, off sc1

.LBB0_486:
	ds_bpermute_b32 v48, v158, v77
	s_waitcnt lgkmcnt(0)
	v_add_f32_e32 v48, v77, v48
	ds_bpermute_b32 v49, v159, v48
	s_and_saveexec_b64 s[76:77], s[10:11]
	s_cbranch_execz .LBB0_488
	s_waitcnt lgkmcnt(0)
	v_add_f32_e32 v50, v48, v49
	s_cmp_eq_u32 s36, 1
	v_lshlrev_b64 v[48:49], 6, v[64:65]
	s_cselect_b32 s78, 32, 48
	s_mov_b32 s79, s39
	v_lshl_add_u64 v[48:49], s[52:53], 0, v[48:49]
	v_lshl_add_u64 v[48:49], v[48:49], 0, s[78:79]
	s_lshl_b32 s78, s25, 2
	v_lshl_add_u64 v[48:49], v[48:49], 0, s[78:79]
	global_store_dword v[48:49], v50, off sc1

.LBB0_539:
	ds_bpermute_b32 v32, v158, v60
	s_waitcnt lgkmcnt(0)
	v_add_f32_e32 v32, v60, v32
	ds_bpermute_b32 v33, v159, v32
	s_and_saveexec_b64 s[76:77], s[10:11]
	s_cbranch_execz .LBB0_541
	s_waitcnt lgkmcnt(0)
	v_add_f32_e32 v34, v32, v33
	s_cmp_eq_u32 s36, 0
	v_lshlrev_b64 v[32:33], 6, v[48:49]
	s_cselect_b32 s78, 0, 16
	s_mov_b32 s79, s39
	v_lshl_add_u64 v[32:33], s[52:53], 0, v[32:33]
	v_lshl_add_u64 v[32:33], v[32:33], 0, s[78:79]
	s_lshl_b32 s78, s25, 2
	v_lshl_add_u64 v[32:33], v[32:33], 0, s[78:79]
	global_store_dword v[32:33], v34, off sc1

.LBB0_542:
	ds_bpermute_b32 v32, v158, v61
	s_waitcnt lgkmcnt(0)
	v_add_f32_e32 v32, v61, v32
	ds_bpermute_b32 v33, v159, v32
	s_and_saveexec_b64 s[76:77], s[10:11]
	s_cbranch_execz .LBB0_544
	s_waitcnt lgkmcnt(0)
	v_add_f32_e32 v34, v32, v33
	s_cmp_eq_u32 s36, 1
	v_lshlrev_b64 v[32:33], 6, v[48:49]
	s_cselect_b32 s78, 32, 48
	s_mov_b32 s79, s39
	v_lshl_add_u64 v[32:33], s[52:53], 0, v[32:33]
	v_lshl_add_u64 v[32:33], v[32:33], 0, s[78:79]
	s_lshl_b32 s78, s25, 2
	v_lshl_add_u64 v[32:33], v[32:33], 0, s[78:79]
	global_store_dword v[32:33], v34, off sc1

.LBB0_595:
	ds_bpermute_b32 v16, v158, v44
	s_waitcnt lgkmcnt(0)
	v_add_f32_e32 v16, v44, v16
	ds_bpermute_b32 v17, v159, v16
	s_and_saveexec_b64 s[76:77], s[10:11]
	s_cbranch_execz .LBB0_597
	s_waitcnt lgkmcnt(0)
	v_add_f32_e32 v18, v16, v17
	s_cmp_eq_u32 s36, 0
	v_lshlrev_b64 v[16:17], 6, v[32:33]
	s_cselect_b32 s78, 0, 16
	s_mov_b32 s79, s39
	v_lshl_add_u64 v[16:17], s[52:53], 0, v[16:17]
	v_lshl_add_u64 v[16:17], v[16:17], 0, s[78:79]
	s_lshl_b32 s78, s25, 2
	v_lshl_add_u64 v[16:17], v[16:17], 0, s[78:79]
	global_store_dword v[16:17], v18, off sc1

.LBB0_598:
	ds_bpermute_b32 v16, v158, v45
	s_waitcnt lgkmcnt(0)
	v_add_f32_e32 v16, v45, v16
	ds_bpermute_b32 v17, v159, v16
	s_and_saveexec_b64 s[76:77], s[10:11]
	s_cbranch_execz .LBB0_600
	s_waitcnt lgkmcnt(0)
	v_add_f32_e32 v18, v16, v17
	s_cmp_eq_u32 s36, 1
	v_lshlrev_b64 v[16:17], 6, v[32:33]
	s_cselect_b32 s78, 32, 48
	s_mov_b32 s79, s39
	v_lshl_add_u64 v[16:17], s[52:53], 0, v[16:17]
	v_lshl_add_u64 v[16:17], v[16:17], 0, s[78:79]
	s_lshl_b32 s78, s25, 2
	v_lshl_add_u64 v[16:17], v[16:17], 0, s[78:79]
	global_store_dword v[16:17], v18, off sc1

.LBB0_651:
	ds_bpermute_b32 v0, v158, v28
	s_waitcnt lgkmcnt(0)
	v_add_f32_e32 v0, v28, v0
	ds_bpermute_b32 v1, v159, v0
	s_and_saveexec_b64 s[6:7], s[10:11]
	s_cbranch_execz .LBB0_653
	s_waitcnt lgkmcnt(0)
	v_add_f32_e32 v2, v0, v1
	s_cmp_eq_u32 s36, 0
	v_lshlrev_b64 v[0:1], 6, v[16:17]
	s_cselect_b32 s38, 0, 16
	v_lshl_add_u64 v[0:1], s[52:53], 0, v[0:1]
	v_lshl_add_u64 v[0:1], v[0:1], 0, s[38:39]
	s_lshl_b32 s38, s25, 2
	v_lshl_add_u64 v[0:1], v[0:1], 0, s[38:39]
	global_store_dword v[0:1], v2, off sc1

.LBB0_654:
	ds_bpermute_b32 v0, v158, v29
	s_waitcnt lgkmcnt(0)
	v_add_f32_e32 v0, v29, v0
	ds_bpermute_b32 v1, v159, v0
	s_and_saveexec_b64 s[6:7], s[10:11]
	s_cbranch_execz .LBB0_656
	s_waitcnt lgkmcnt(0)
	v_add_f32_e32 v2, v0, v1
	s_cmp_eq_u32 s36, 1
	v_lshlrev_b64 v[0:1], 6, v[16:17]
	s_cselect_b32 s38, 32, 48
	v_lshl_add_u64 v[0:1], s[52:53], 0, v[0:1]
	v_lshl_add_u64 v[0:1], v[0:1], 0, s[38:39]
	s_lshl_b32 s38, s25, 2
	v_lshl_add_u64 v[0:1], v[0:1], 0, s[38:39]
	global_store_dword v[0:1], v2, off sc1

.LBB0_861:
	s_add_u32 s4, s67, s24
	s_addc_u32 s5, s37, 0
	v_rcp_f32_e32 v14, v80
	v_rcp_f32_e32 v87, v4
	v_mov_b32_e32 v4, v229
	s_lshl_b64 s[4:5], s[4:5], 11
	s_add_u32 s4, s65, s4
	v_and_b32_e32 v0, 31, v4
	s_addc_u32 s5, s66, s5
	v_lshlrev_b32_e32 v0, 1, v0
	v_rcp_f32_e32 v85, v2
	v_rcp_f32_e32 v86, v3
	v_lshl_add_u64 v[2:3], s[4:5], 0, v[0:1]
	v_lshlrev_b32_e32 v0, 7, v4
	v_and_b32_e32 v4, 0xfffff000, v0
	v_mul_f32_e32 v0, v14, v64
	v_rcp_f32_e32 v80, v82
	v_rcp_f32_e32 v82, v6
	v_rcp_f32_e32 v6, v5
	v_bfe_u32 v5, v0, 16, 1
	v_add3_u32 v0, v0, v5, s30
	v_ashrrev_i32_e32 v5, 31, v4
	v_rcp_f32_e32 v15, v81
	v_rcp_f32_e32 v81, v83
	v_rcp_f32_e32 v83, v8
	v_rcp_f32_e32 v84, v9
	v_lshl_add_u64 v[8:9], v[4:5], 1, v[2:3]
	global_store_short_d16_hi v[8:9], v0, off sc1
	v_mul_f32_e32 v0, v14, v48
	v_bfe_u32 v5, v0, 16, 1
	v_add3_u32 v0, v0, v5, s30
	global_store_short_d16_hi v[8:9], v0, off offset:64 sc1
	v_mul_f32_e32 v0, v14, v32
	v_bfe_u32 v5, v0, 16, 1
	v_add3_u32 v0, v0, v5, s30
	global_store_short_d16_hi v[8:9], v0, off offset:128 sc1
	v_mul_f32_e32 v0, v14, v16
	v_bfe_u32 v5, v0, 16, 1
	v_add3_u32 v0, v0, v5, s30
	global_store_short_d16_hi v[8:9], v0, off offset:192 sc1
	v_mul_f32_e32 v0, v15, v65
	v_bfe_u32 v5, v0, 16, 1
	v_add3_u32 v0, v0, v5, s30
	global_store_short_d16_hi v[8:9], v0, off offset:2048 sc1
	v_mul_f32_e32 v0, v15, v49
	v_bfe_u32 v5, v0, 16, 1
	v_add3_u32 v0, v0, v5, s30
	global_store_short_d16_hi v[8:9], v0, off offset:2112 sc1
	v_mul_f32_e32 v0, v15, v33
	v_bfe_u32 v5, v0, 16, 1
	v_add3_u32 v0, v0, v5, s30
	global_store_short_d16_hi v[8:9], v0, off offset:2176 sc1
	v_mul_f32_e32 v0, v15, v17
	v_bfe_u32 v5, v0, 16, 1
	v_add3_u32 v0, v0, v5, s30
	global_store_short_d16_hi v[8:9], v0, off offset:2240 sc1
	v_or_b32_e32 v8, 0x800, v4
	v_mul_f32_e32 v0, v80, v66
	v_bfe_u32 v5, v0, 16, 1
	v_ashrrev_i32_e32 v9, 31, v8
	v_add3_u32 v0, v0, v5, s30
	v_lshl_add_u64 v[8:9], v[8:9], 1, v[2:3]
	global_store_short_d16_hi v[8:9], v0, off sc1
	v_mul_f32_e32 v0, v80, v50
	v_bfe_u32 v5, v0, 16, 1
	v_add3_u32 v0, v0, v5, s30
	global_store_short_d16_hi v[8:9], v0, off offset:64 sc1
	v_mul_f32_e32 v0, v80, v34
	v_bfe_u32 v5, v0, 16, 1
	v_add3_u32 v0, v0, v5, s30
	global_store_short_d16_hi v[8:9], v0, off offset:128 sc1
	v_mul_f32_e32 v0, v80, v18
	v_bfe_u32 v5, v0, 16, 1
	v_add3_u32 v0, v0, v5, s30
	global_store_short_d16_hi v[8:9], v0, off offset:192 sc1
	v_or_b32_e32 v8, 0xc00, v4
	v_mul_f32_e32 v0, v81, v67
	v_bfe_u32 v5, v0, 16, 1
	v_ashrrev_i32_e32 v9, 31, v8
	v_add3_u32 v0, v0, v5, s30
	v_lshl_add_u64 v[8:9], v[8:9], 1, v[2:3]
	global_store_short_d16_hi v[8:9], v0, off sc1
	v_mul_f32_e32 v0, v81, v51
	v_bfe_u32 v5, v0, 16, 1
	v_add3_u32 v0, v0, v5, s30
	global_store_short_d16_hi v[8:9], v0, off offset:64 sc1
	v_mul_f32_e32 v0, v81, v35
	v_bfe_u32 v5, v0, 16, 1
	v_rcp_f32_e32 v10, v10
	v_add3_u32 v0, v0, v5, s30
	global_store_short_d16_hi v[8:9], v0, off offset:128 sc1
	v_mul_f32_e32 v0, v81, v19
	v_bfe_u32 v5, v0, 16, 1
	v_add3_u32 v0, v0, v5, s30
	global_store_short_d16_hi v[8:9], v0, off offset:192 sc1
	v_add_u32_e32 v8, 0x2000, v4
	v_mul_f32_e32 v0, v10, v68
	v_bfe_u32 v5, v0, 16, 1
	v_ashrrev_i32_e32 v9, 31, v8
	v_add3_u32 v0, v0, v5, s30
	v_lshl_add_u64 v[8:9], v[8:9], 1, v[2:3]
	global_store_short_d16_hi v[8:9], v0, off sc1
	v_mul_f32_e32 v0, v10, v52
	v_add_u32_e32 v8, 0x2020, v4
	v_bfe_u32 v5, v0, 16, 1
	v_ashrrev_i32_e32 v9, 31, v8
	v_add3_u32 v0, v0, v5, s30
	v_lshl_add_u64 v[8:9], v[8:9], 1, v[2:3]
	global_store_short_d16_hi v[8:9], v0, off sc1
	v_mul_f32_e32 v0, v10, v36
	v_add_u32_e32 v8, 0x2040, v4
	v_bfe_u32 v5, v0, 16, 1
	v_ashrrev_i32_e32 v9, 31, v8
	v_rcp_f32_e32 v11, v11
	v_add3_u32 v0, v0, v5, s30
	v_lshl_add_u64 v[8:9], v[8:9], 1, v[2:3]
	global_store_short_d16_hi v[8:9], v0, off sc1
	v_mul_f32_e32 v0, v10, v20
	v_add_u32_e32 v8, 0x2060, v4
	v_bfe_u32 v5, v0, 16, 1
	v_ashrrev_i32_e32 v9, 31, v8
	v_add3_u32 v0, v0, v5, s30
	v_lshl_add_u64 v[8:9], v[8:9], 1, v[2:3]
	global_store_short_d16_hi v[8:9], v0, off sc1
	v_add_u32_e32 v8, 0x2400, v4
	v_mul_f32_e32 v0, v11, v69
	v_bfe_u32 v5, v0, 16, 1
	v_ashrrev_i32_e32 v9, 31, v8
	v_add3_u32 v0, v0, v5, s30
	v_lshl_add_u64 v[8:9], v[8:9], 1, v[2:3]
	global_store_short_d16_hi v[8:9], v0, off sc1
	v_mul_f32_e32 v0, v11, v53
	v_add_u32_e32 v8, 0x2420, v4
	v_bfe_u32 v5, v0, 16, 1
	v_ashrrev_i32_e32 v9, 31, v8
	v_add3_u32 v0, v0, v5, s30
	v_lshl_add_u64 v[8:9], v[8:9], 1, v[2:3]
	global_store_short_d16_hi v[8:9], v0, off sc1
	v_mul_f32_e32 v0, v11, v37
	v_add_u32_e32 v8, 0x2440, v4
	v_bfe_u32 v5, v0, 16, 1
	v_ashrrev_i32_e32 v9, 31, v8
	v_rcp_f32_e32 v12, v12
	v_add3_u32 v0, v0, v5, s30
	v_lshl_add_u64 v[8:9], v[8:9], 1, v[2:3]
	global_store_short_d16_hi v[8:9], v0, off sc1
	v_mul_f32_e32 v0, v11, v21
	v_add_u32_e32 v8, 0x2460, v4
	v_bfe_u32 v5, v0, 16, 1
	v_ashrrev_i32_e32 v9, 31, v8
	v_add3_u32 v0, v0, v5, s30
	v_lshl_add_u64 v[8:9], v[8:9], 1, v[2:3]
	global_store_short_d16_hi v[8:9], v0, off sc1
	v_add_u32_e32 v8, 0x2800, v4
	v_mul_f32_e32 v0, v12, v70
	v_bfe_u32 v5, v0, 16, 1
	v_ashrrev_i32_e32 v9, 31, v8
	v_add3_u32 v0, v0, v5, s30
	v_lshl_add_u64 v[8:9], v[8:9], 1, v[2:3]
	global_store_short_d16_hi v[8:9], v0, off sc1
	v_mul_f32_e32 v0, v12, v54
	v_add_u32_e32 v8, 0x2820, v4
	v_bfe_u32 v5, v0, 16, 1
	v_ashrrev_i32_e32 v9, 31, v8
	v_add3_u32 v0, v0, v5, s30
	v_lshl_add_u64 v[8:9], v[8:9], 1, v[2:3]
	global_store_short_d16_hi v[8:9], v0, off sc1
	v_mul_f32_e32 v0, v12, v38
	v_add_u32_e32 v8, 0x2840, v4
	v_bfe_u32 v5, v0, 16, 1
	v_ashrrev_i32_e32 v9, 31, v8
	v_rcp_f32_e32 v13, v13
	v_add3_u32 v0, v0, v5, s30
	v_lshl_add_u64 v[8:9], v[8:9], 1, v[2:3]
	global_store_short_d16_hi v[8:9], v0, off sc1
	v_mul_f32_e32 v0, v12, v22
	v_add_u32_e32 v8, 0x2860, v4
	v_bfe_u32 v5, v0, 16, 1
	v_ashrrev_i32_e32 v9, 31, v8
	v_add3_u32 v0, v0, v5, s30
	v_lshl_add_u64 v[8:9], v[8:9], 1, v[2:3]
	global_store_short_d16_hi v[8:9], v0, off sc1
	v_add_u32_e32 v8, 0x2c00, v4
	v_mul_f32_e32 v0, v13, v71
	v_bfe_u32 v5, v0, 16, 1
	v_ashrrev_i32_e32 v9, 31, v8
	v_add3_u32 v0, v0, v5, s30
	v_lshl_add_u64 v[8:9], v[8:9], 1, v[2:3]
	global_store_short_d16_hi v[8:9], v0, off sc1
	v_mul_f32_e32 v0, v13, v55
	v_add_u32_e32 v8, 0x2c20, v4
	v_bfe_u32 v5, v0, 16, 1
	v_ashrrev_i32_e32 v9, 31, v8
	v_add3_u32 v0, v0, v5, s30
	v_lshl_add_u64 v[8:9], v[8:9], 1, v[2:3]
	global_store_short_d16_hi v[8:9], v0, off sc1
	v_mul_f32_e32 v0, v13, v39
	v_add_u32_e32 v8, 0x2c40, v4
	v_bfe_u32 v5, v0, 16, 1
	v_ashrrev_i32_e32 v9, 31, v8
	v_add3_u32 v0, v0, v5, s30
	v_lshl_add_u64 v[8:9], v[8:9], 1, v[2:3]
	global_store_short_d16_hi v[8:9], v0, off sc1
	v_mul_f32_e32 v0, v13, v23
	v_add_u32_e32 v8, 0x2c60, v4
	v_bfe_u32 v5, v0, 16, 1
	v_ashrrev_i32_e32 v9, 31, v8
	v_add3_u32 v0, v0, v5, s30
	v_lshl_add_u64 v[8:9], v[8:9], 1, v[2:3]
	global_store_short_d16_hi v[8:9], v0, off sc1
	v_add_u32_e32 v8, 0x4000, v4
	v_mul_f32_e32 v0, v82, v72
	v_bfe_u32 v5, v0, 16, 1
	v_ashrrev_i32_e32 v9, 31, v8
	v_add3_u32 v0, v0, v5, s30
	v_lshl_add_u64 v[8:9], v[8:9], 1, v[2:3]
	global_store_short_d16_hi v[8:9], v0, off sc1
	v_mul_f32_e32 v0, v82, v56
	v_add_u32_e32 v8, 0x4020, v4
	v_bfe_u32 v5, v0, 16, 1
	v_ashrrev_i32_e32 v9, 31, v8
	v_add3_u32 v0, v0, v5, s30
	v_lshl_add_u64 v[8:9], v[8:9], 1, v[2:3]
	global_store_short_d16_hi v[8:9], v0, off sc1
	v_mul_f32_e32 v0, v82, v40
	v_add_u32_e32 v8, 0x4040, v4
	v_bfe_u32 v5, v0, 16, 1
	v_ashrrev_i32_e32 v9, 31, v8
	v_rcp_f32_e32 v7, v7
	v_add3_u32 v0, v0, v5, s30
	v_lshl_add_u64 v[8:9], v[8:9], 1, v[2:3]
	global_store_short_d16_hi v[8:9], v0, off sc1
	v_mul_f32_e32 v0, v82, v24
	v_add_u32_e32 v8, 0x4060, v4
	v_bfe_u32 v5, v0, 16, 1
	v_ashrrev_i32_e32 v9, 31, v8
	v_add3_u32 v0, v0, v5, s30
	v_lshl_add_u64 v[8:9], v[8:9], 1, v[2:3]
	global_store_short_d16_hi v[8:9], v0, off sc1
	v_add_u32_e32 v8, 0x4400, v4
	v_mul_f32_e32 v0, v7, v73
	v_bfe_u32 v5, v0, 16, 1
	v_ashrrev_i32_e32 v9, 31, v8
	v_add3_u32 v0, v0, v5, s30
	v_lshl_add_u64 v[8:9], v[8:9], 1, v[2:3]
	global_store_short_d16_hi v[8:9], v0, off sc1
	v_mul_f32_e32 v0, v7, v57
	v_add_u32_e32 v8, 0x4420, v4
	v_bfe_u32 v5, v0, 16, 1
	v_ashrrev_i32_e32 v9, 31, v8
	v_add3_u32 v0, v0, v5, s30
	v_lshl_add_u64 v[8:9], v[8:9], 1, v[2:3]
	global_store_short_d16_hi v[8:9], v0, off sc1
	v_mul_f32_e32 v0, v7, v41
	v_add_u32_e32 v8, 0x4440, v4
	v_bfe_u32 v5, v0, 16, 1
	v_ashrrev_i32_e32 v9, 31, v8
	v_add3_u32 v0, v0, v5, s30
	v_lshl_add_u64 v[8:9], v[8:9], 1, v[2:3]
	global_store_short_d16_hi v[8:9], v0, off sc1
	v_mul_f32_e32 v0, v7, v25
	v_add_u32_e32 v8, 0x4460, v4
	v_bfe_u32 v5, v0, 16, 1
	v_ashrrev_i32_e32 v9, 31, v8
	v_add3_u32 v0, v0, v5, s30
	v_lshl_add_u64 v[8:9], v[8:9], 1, v[2:3]
	global_store_short_d16_hi v[8:9], v0, off sc1
	v_add_u32_e32 v8, 0x4800, v4
	v_mul_f32_e32 v0, v83, v74
	v_bfe_u32 v5, v0, 16, 1
	v_ashrrev_i32_e32 v9, 31, v8
	v_add3_u32 v0, v0, v5, s30
	v_lshl_add_u64 v[8:9], v[8:9], 1, v[2:3]
	global_store_short_d16_hi v[8:9], v0, off sc1
	v_mul_f32_e32 v0, v83, v58
	v_add_u32_e32 v8, 0x4820, v4
	v_bfe_u32 v5, v0, 16, 1
	v_ashrrev_i32_e32 v9, 31, v8
	v_add3_u32 v0, v0, v5, s30
	v_lshl_add_u64 v[8:9], v[8:9], 1, v[2:3]
	global_store_short_d16_hi v[8:9], v0, off sc1
	v_mul_f32_e32 v0, v83, v42
	v_add_u32_e32 v8, 0x4840, v4
	v_bfe_u32 v5, v0, 16, 1
	v_ashrrev_i32_e32 v9, 31, v8
	v_add3_u32 v0, v0, v5, s30
	v_lshl_add_u64 v[8:9], v[8:9], 1, v[2:3]
	global_store_short_d16_hi v[8:9], v0, off sc1
	v_mul_f32_e32 v0, v83, v26
	v_add_u32_e32 v8, 0x4860, v4
	v_bfe_u32 v5, v0, 16, 1
	v_ashrrev_i32_e32 v9, 31, v8
	v_add3_u32 v0, v0, v5, s30
	v_lshl_add_u64 v[8:9], v[8:9], 1, v[2:3]
	global_store_short_d16_hi v[8:9], v0, off sc1
	v_add_u32_e32 v8, 0x4c00, v4
	v_mul_f32_e32 v0, v84, v75
	v_bfe_u32 v5, v0, 16, 1
	v_ashrrev_i32_e32 v9, 31, v8
	v_add3_u32 v0, v0, v5, s30
	v_lshl_add_u64 v[8:9], v[8:9], 1, v[2:3]
	global_store_short_d16_hi v[8:9], v0, off sc1
	v_mul_f32_e32 v0, v84, v59
	v_add_u32_e32 v8, 0x4c20, v4
	v_bfe_u32 v5, v0, 16, 1
	v_ashrrev_i32_e32 v9, 31, v8
	v_add3_u32 v0, v0, v5, s30
	v_lshl_add_u64 v[8:9], v[8:9], 1, v[2:3]
	global_store_short_d16_hi v[8:9], v0, off sc1
	v_mul_f32_e32 v0, v84, v43
	v_add_u32_e32 v8, 0x4c40, v4
	v_bfe_u32 v5, v0, 16, 1
	v_ashrrev_i32_e32 v9, 31, v8
	v_add3_u32 v0, v0, v5, s30
	v_lshl_add_u64 v[8:9], v[8:9], 1, v[2:3]
	global_store_short_d16_hi v[8:9], v0, off sc1
	v_mul_f32_e32 v0, v84, v27
	v_add_u32_e32 v8, 0x4c60, v4
	v_bfe_u32 v5, v0, 16, 1
	v_ashrrev_i32_e32 v9, 31, v8
	v_add3_u32 v0, v0, v5, s30
	v_lshl_add_u64 v[8:9], v[8:9], 1, v[2:3]
	global_store_short_d16_hi v[8:9], v0, off sc1
	v_add_u32_e32 v8, 0x6000, v4
	v_mul_f32_e32 v0, v85, v76
	v_bfe_u32 v5, v0, 16, 1
	v_ashrrev_i32_e32 v9, 31, v8
	v_add3_u32 v0, v0, v5, s30
	v_lshl_add_u64 v[8:9], v[8:9], 1, v[2:3]
	global_store_short_d16_hi v[8:9], v0, off sc1
	v_mul_f32_e32 v0, v85, v60
	v_add_u32_e32 v8, 0x6020, v4
	v_bfe_u32 v5, v0, 16, 1
	v_ashrrev_i32_e32 v9, 31, v8
	v_add3_u32 v0, v0, v5, s30
	v_lshl_add_u64 v[8:9], v[8:9], 1, v[2:3]
	global_store_short_d16_hi v[8:9], v0, off sc1
	v_mul_f32_e32 v0, v85, v44
	v_add_u32_e32 v8, 0x6040, v4
	v_bfe_u32 v5, v0, 16, 1
	v_ashrrev_i32_e32 v9, 31, v8
	v_add3_u32 v0, v0, v5, s30
	v_lshl_add_u64 v[8:9], v[8:9], 1, v[2:3]
	global_store_short_d16_hi v[8:9], v0, off sc1
	v_mul_f32_e32 v0, v85, v28
	v_add_u32_e32 v8, 0x6060, v4
	v_bfe_u32 v5, v0, 16, 1
	v_ashrrev_i32_e32 v9, 31, v8
	v_add3_u32 v0, v0, v5, s30
	v_lshl_add_u64 v[8:9], v[8:9], 1, v[2:3]
	global_store_short_d16_hi v[8:9], v0, off sc1
	v_add_u32_e32 v8, 0x6400, v4
	v_mul_f32_e32 v0, v86, v77
	v_bfe_u32 v5, v0, 16, 1
	v_ashrrev_i32_e32 v9, 31, v8
	v_add3_u32 v0, v0, v5, s30
	v_lshl_add_u64 v[8:9], v[8:9], 1, v[2:3]
	global_store_short_d16_hi v[8:9], v0, off sc1
	v_mul_f32_e32 v0, v86, v61
	v_add_u32_e32 v8, 0x6420, v4
	v_bfe_u32 v5, v0, 16, 1
	v_ashrrev_i32_e32 v9, 31, v8
	v_add3_u32 v0, v0, v5, s30
	v_lshl_add_u64 v[8:9], v[8:9], 1, v[2:3]
	global_store_short_d16_hi v[8:9], v0, off sc1
	v_mul_f32_e32 v0, v86, v45
	v_add_u32_e32 v8, 0x6440, v4
	v_bfe_u32 v5, v0, 16, 1
	v_ashrrev_i32_e32 v9, 31, v8
	v_add3_u32 v0, v0, v5, s30
	v_lshl_add_u64 v[8:9], v[8:9], 1, v[2:3]
	global_store_short_d16_hi v[8:9], v0, off sc1
	v_mul_f32_e32 v0, v86, v29
	v_add_u32_e32 v8, 0x6460, v4
	v_bfe_u32 v5, v0, 16, 1
	v_ashrrev_i32_e32 v9, 31, v8
	v_add3_u32 v0, v0, v5, s30
	v_lshl_add_u64 v[8:9], v[8:9], 1, v[2:3]
	global_store_short_d16_hi v[8:9], v0, off sc1
	v_add_u32_e32 v8, 0x6800, v4
	v_mul_f32_e32 v0, v87, v78
	v_bfe_u32 v5, v0, 16, 1
	v_ashrrev_i32_e32 v9, 31, v8
	v_add3_u32 v0, v0, v5, s30
	v_lshl_add_u64 v[8:9], v[8:9], 1, v[2:3]
	global_store_short_d16_hi v[8:9], v0, off sc1
	v_mul_f32_e32 v0, v87, v62
	v_add_u32_e32 v8, 0x6820, v4
	v_bfe_u32 v5, v0, 16, 1
	v_ashrrev_i32_e32 v9, 31, v8
	v_add3_u32 v0, v0, v5, s30
	v_lshl_add_u64 v[8:9], v[8:9], 1, v[2:3]
	global_store_short_d16_hi v[8:9], v0, off sc1
	v_mul_f32_e32 v0, v87, v46
	v_add_u32_e32 v8, 0x6840, v4
	v_bfe_u32 v5, v0, 16, 1
	v_ashrrev_i32_e32 v9, 31, v8
	v_add3_u32 v0, v0, v5, s30
	v_lshl_add_u64 v[8:9], v[8:9], 1, v[2:3]
	global_store_short_d16_hi v[8:9], v0, off sc1
	v_mul_f32_e32 v0, v87, v30
	v_add_u32_e32 v8, 0x6860, v4
	v_bfe_u32 v5, v0, 16, 1
	v_ashrrev_i32_e32 v9, 31, v8
	v_add3_u32 v0, v0, v5, s30
	v_lshl_add_u64 v[8:9], v[8:9], 1, v[2:3]
	global_store_short_d16_hi v[8:9], v0, off sc1
	v_add_u32_e32 v8, 0x6c00, v4
	v_mul_f32_e32 v0, v6, v79
	v_bfe_u32 v5, v0, 16, 1
	v_ashrrev_i32_e32 v9, 31, v8
	v_add3_u32 v0, v0, v5, s30
	v_lshl_add_u64 v[8:9], v[8:9], 1, v[2:3]
	global_store_short_d16_hi v[8:9], v0, off sc1
	v_mul_f32_e32 v0, v6, v63
	v_add_u32_e32 v8, 0x6c20, v4
	v_bfe_u32 v5, v0, 16, 1
	v_ashrrev_i32_e32 v9, 31, v8
	v_add3_u32 v0, v0, v5, s30
	v_lshl_add_u64 v[8:9], v[8:9], 1, v[2:3]
	global_store_short_d16_hi v[8:9], v0, off sc1
	v_mul_f32_e32 v0, v6, v47
	v_add_u32_e32 v8, 0x6c40, v4
	v_bfe_u32 v5, v0, 16, 1
	v_ashrrev_i32_e32 v9, 31, v8
	v_add3_u32 v0, v0, v5, s30
	v_lshl_add_u64 v[8:9], v[8:9], 1, v[2:3]
	global_store_short_d16_hi v[8:9], v0, off sc1
	v_mul_f32_e32 v0, v6, v31
	v_bfe_u32 v5, v0, 16, 1
	v_add_u32_e32 v4, 0x6c60, v4
	v_add3_u32 v0, v0, v5, s30
	v_ashrrev_i32_e32 v5, 31, v4
	v_lshl_add_u64 v[2:3], v[4:5], 1, v[2:3]
	s_mov_b64 s[4:5], -1
	s_mov_b64 s[56:57], 0
	s_and_b64 vcc, exec, s[54:55]
	global_store_short_d16_hi v[2:3], v0, off sc1
	s_cbranch_vccnz .LBB0_859

.LBB0_1477:
	v_rcp_f32_e32 v113, v80
	v_rcp_f32_e32 v112, v81
	v_rcp_f32_e32 v111, v82
	v_rcp_f32_e32 v110, v83
	v_rcp_f32_e32 v109, v12
	v_rcp_f32_e32 v108, v13
	v_rcp_f32_e32 v107, v14
	v_rcp_f32_e32 v106, v15
	v_rcp_f32_e32 v105, v8
	v_rcp_f32_e32 v104, v9
	v_rcp_f32_e32 v103, v10
	v_rcp_f32_e32 v102, v11
	v_rcp_f32_e32 v101, v4
	v_rcp_f32_e32 v100, v5
	v_rcp_f32_e32 v99, v6
	v_rcp_f32_e32 v98, v7
	v_mov_b32_e32 v4, v203
	s_mov_b64 s[4:5], -1
	v_ashrrev_i32_e32 v5, 31, v4
	v_lshl_add_u64 v[0:1], v[4:5], 2, s[8:9]
	s_and_b64 vcc, exec, s[48:49]
	s_cbranch_vccz .LBB0_1479
	s_mov_b32 s100, 0xffff0000
	s_mov_b32 s101, 0xffff0000
	s_mov_b32 s4, 0x8000
	v_add_co_u32_e32 v6, vcc, s4, v0
	s_mov_b32 s4, 0x10000
	s_nop 0
	v_addc_co_u32_e32 v7, vcc, 0, v1, vcc
	v_add_co_u32_e32 v118, vcc, s74, v0
	global_load_dword v5, v[0:1], off
	s_nop 0
	v_addc_co_u32_e32 v119, vcc, 0, v1, vcc
	v_add_co_u32_e32 v8, vcc, s4, v0
	s_mov_b32 s4, 0x18000
	s_nop 0
	v_addc_co_u32_e32 v9, vcc, 0, v1, vcc
	v_add_co_u32_e32 v120, vcc, s73, v0
	global_load_dword v140, v[118:119], off offset:-4096
	s_nop 0
	v_addc_co_u32_e32 v121, vcc, 0, v1, vcc
	v_add_co_u32_e32 v10, vcc, s4, v0
	global_load_dword v130, v[120:121], off offset:-4096
	s_nop 0
	v_addc_co_u32_e32 v11, vcc, 0, v1, vcc
	v_add_co_u32_e32 v122, vcc, s72, v0
	s_movk_i32 s4, 0x1000
	s_nop 0
	v_addc_co_u32_e32 v123, vcc, 0, v1, vcc
	global_load_dword v114, v[122:123], off offset:-4096
	global_load_dword v115, v[10:11], off offset:2048
	global_load_dword v131, v[8:9], off offset:2048
	global_load_dword v142, v[6:7], off offset:2048
	s_nop 0
	global_load_dword v8, v[0:1], off offset:2048
	v_add_co_u32_e32 v124, vcc, s4, v0
	s_movk_i32 s4, 0x2000
	s_nop 0
	v_addc_co_u32_e32 v125, vcc, 0, v1, vcc
	v_add_co_u32_e32 v6, vcc, s4, v0
	global_load_dword v116, v[122:123], off
	global_load_dword v132, v[120:121], off
	global_load_dword v143, v[118:119], off
	v_addc_co_u32_e32 v7, vcc, 0, v1, vcc
	global_load_dword v9, v[6:7], off offset:-4096
	global_load_dword v117, v[122:123], off offset:2048
	global_load_dword v133, v[120:121], off offset:2048
	global_load_dword v146, v[118:119], off offset:2048
	global_load_dword v10, v[124:125], off offset:2048
	v_add_co_u32_e32 v120, vcc, s75, v0
	v_mul_f32_e64 v12, v112, -v204
	s_nop 0
	v_addc_co_u32_e32 v121, vcc, 0, v1, vcc
	v_add_co_u32_e32 v122, vcc, s84, v0
	v_mul_f32_e64 v14, v109, -v204
	s_nop 0
	v_addc_co_u32_e32 v123, vcc, 0, v1, vcc
	v_add_co_u32_e32 v124, vcc, s76, v0
	s_movk_i32 s4, 0x4000
	s_nop 0
	v_addc_co_u32_e32 v125, vcc, 0, v1, vcc
	v_add_co_u32_e32 v126, vcc, s79, v0
	v_mul_f32_e64 v80, v108, -v204
	s_nop 0
	v_addc_co_u32_e32 v127, vcc, 0, v1, vcc
	v_add_co_u32_e32 v138, vcc, s77, v0
	v_mul_f32_e64 v82, v107, -v204
	s_nop 0
	v_addc_co_u32_e32 v139, vcc, 0, v1, vcc
	v_add_co_u32_e32 v144, vcc, s78, v0
	v_mul_f32_e64 v84, v106, -v204
	s_nop 0
	v_addc_co_u32_e32 v145, vcc, 0, v1, vcc
	v_mul_f32_e64 v86, v105, -v204
	v_mul_f32_e64 v88, v104, -v204
	v_mul_f32_e64 v90, v103, -v204
	v_mul_f32_e64 v92, v102, -v204
	v_mul_f32_e64 v94, v101, -v204
	v_mul_f32_e64 v96, v100, -v204
	v_mul_f32_e64 v129, v99, -v204
	v_mul_f32_e64 v2, v113, -v204
	v_mul_f32_e64 v134, v98, -v204
	v_mul_f32_e64 v15, v111, -v204
	v_mul_f32_e64 v83, v110, -v204
	global_load_dword v155, v[122:123], off offset:-4096
	global_load_dword v136, v[126:127], off offset:-4096
	global_load_dword v119, v[144:145], off offset:-4096
	v_lshlrev_b32_e32 v245, 2, v203
	s_add_u32 s98, s8, 0x3000
	s_addc_u32 s99, s9, 0
	global_load_dword v184, v245, s[98:99] offset:-4096
	global_load_dword v190, v245, s[98:99] offset:-2048
	global_load_dword v194, v245, s[98:99]
	global_load_dword v212, v245, s[98:99] offset:2048
	s_add_u32 s98, s8, 0x5000
	s_addc_u32 s99, s9, 0
	global_load_dword v215, v245, s[98:99] offset:-4096
	global_load_dword v220, v245, s[98:99] offset:-2048
	global_load_dword v224, v245, s[98:99]
	global_load_dword v229, v245, s[98:99] offset:2048
	s_add_u32 s98, s8, 0x7000
	s_addc_u32 s99, s9, 0
	global_load_dword v233, v245, s[98:99] offset:-4096
	global_load_dword v237, v245, s[98:99] offset:-2048
	global_load_dword v241, v245, s[98:99]
	global_load_dword v247, v245, s[98:99] offset:2048
	s_add_u32 s98, s8, 0xb000
	s_addc_u32 s99, s9, 0
	global_load_dword v189, v245, s[98:99] offset:-2048
	global_load_dword v193, v245, s[98:99]
	global_load_dword v197, v245, s[98:99] offset:2048
	s_add_u32 s98, s8, 0xd000
	s_addc_u32 s99, s9, 0
	global_load_dword v213, v245, s[98:99] offset:-4096
	global_load_dword v219, v245, s[98:99] offset:-2048
	global_load_dword v223, v245, s[98:99]
	global_load_dword v227, v245, s[98:99] offset:2048
	s_add_u32 s98, s8, 0xf000
	s_addc_u32 s99, s9, 0
	global_load_dword v230, v245, s[98:99] offset:-4096
	global_load_dword v236, v245, s[98:99] offset:-2048
	global_load_dword v240, v245, s[98:99]
	global_load_dword v246, v245, s[98:99] offset:2048
	s_add_u32 s98, s8, 0x13000
	s_addc_u32 s99, s9, 0
	global_load_dword v188, v245, s[98:99] offset:-2048
	global_load_dword v192, v245, s[98:99]
	global_load_dword v196, v245, s[98:99] offset:2048
	s_add_u32 s98, s8, 0x15000
	s_addc_u32 s99, s9, 0
	global_load_dword v214, v245, s[98:99] offset:-4096
	global_load_dword v218, v245, s[98:99] offset:-2048
	global_load_dword v222, v245, s[98:99]
	global_load_dword v226, v245, s[98:99] offset:2048
	s_add_u32 s98, s8, 0x17000
	s_addc_u32 s99, s9, 0
	global_load_dword v231, v245, s[98:99] offset:-4096
	global_load_dword v235, v245, s[98:99] offset:-2048
	global_load_dword v239, v245, s[98:99]
	global_load_dword v243, v245, s[98:99] offset:2048
	s_add_u32 s98, s8, 0x1b000
	s_addc_u32 s99, s9, 0
	global_load_dword v185, v245, s[98:99] offset:-2048
	global_load_dword v191, v245, s[98:99]
	global_load_dword v195, v245, s[98:99] offset:2048
	s_add_u32 s98, s8, 0x1d000
	s_addc_u32 s99, s9, 0
	global_load_dword v216, v245, s[98:99] offset:-4096
	global_load_dword v217, v245, s[98:99] offset:-2048
	global_load_dword v221, v245, s[98:99]
	global_load_dword v225, v245, s[98:99] offset:2048
	s_add_u32 s98, s8, 0x1f000
	s_addc_u32 s99, s9, 0
	global_load_dword v232, v245, s[98:99] offset:-4096
	global_load_dword v234, v245, s[98:99] offset:-2048
	global_load_dword v238, v245, s[98:99]
	global_load_dword v242, v245, s[98:99] offset:2048
	s_waitcnt vmcnt(0)
	v_fmac_f32_e32 v5, v2, v64
	v_fmac_f32_e32 v140, v2, v48
	v_mul_f32_e32 v13, v140, v140
	v_fmac_f32_e32 v13, v5, v5
	v_fmac_f32_e32 v130, v2, v32
	v_fmac_f32_e32 v13, v130, v130
	v_fmac_f32_e32 v115, v12, v17
	v_fmac_f32_e32 v131, v12, v33
	v_fmac_f32_e32 v142, v12, v49
	v_fmac_f32_e32 v8, v12, v65
	v_mov_b32_e32 v12, v184
	v_fmac_f32_e32 v114, v2, v16
	v_fmac_f32_e32 v13, v114, v114
	v_mul_f32_e32 v11, v142, v142
	v_fmac_f32_e32 v11, v8, v8
	v_fmac_f32_e32 v11, v131, v131
	v_fmac_f32_e32 v11, v115, v115
	v_fmac_f32_e32 v143, v15, v50
	v_mul_f32_e32 v2, v143, v143
	v_fmac_f32_e32 v132, v15, v34
	v_fmac_f32_e32 v9, v15, v66
	v_fmac_f32_e32 v2, v9, v9
	v_fmac_f32_e32 v2, v132, v132
	v_fmac_f32_e32 v116, v15, v18
	v_fmac_f32_e32 v2, v116, v116
	v_fmac_f32_e32 v146, v83, v51
	v_fmac_f32_e32 v10, v83, v67
	v_mul_f32_e32 v81, v146, v146
	v_fmac_f32_e32 v81, v10, v10
	v_fmac_f32_e32 v133, v83, v35
	v_fmac_f32_e32 v81, v133, v133
	v_fmac_f32_e32 v117, v83, v19
	v_fmac_f32_e32 v81, v117, v117
	v_fmac_f32_e32 v155, v14, v52
	v_fmac_f32_e32 v136, v14, v36
	v_fmac_f32_e32 v119, v14, v20
	v_mul_f32_e32 v83, v155, v155
	s_waitcnt vmcnt(0)
	v_fmac_f32_e32 v12, v14, v68
	v_mov_b32_e32 v118, v185
	s_nop 0
	v_mov_b32_e32 v138, v188
	v_mov_b32_e32 v157, v189
	v_mov_b32_e32 v14, v190
	v_add_co_u32_e32 v6, vcc, s85, v0
	v_mov_b32_e32 v120, v191
	v_mov_b32_e32 v139, v192
	v_mov_b32_e32 v158, v193
	v_addc_co_u32_e32 v7, vcc, 0, v1, vcc
	v_add_co_u32_e32 v124, vcc, s4, v0
	s_mov_b32 s4, 0xc000
	s_nop 0
	v_addc_co_u32_e32 v125, vcc, 0, v1, vcc
	v_fmac_f32_e32 v83, v12, v12
	v_fmac_f32_e32 v83, v136, v136
	v_fmac_f32_e32 v83, v119, v119
	s_waitcnt vmcnt(0)
	v_fmac_f32_e32 v118, v80, v21
	v_fmac_f32_e32 v138, v80, v37
	v_fmac_f32_e32 v157, v80, v53
	v_fmac_f32_e32 v14, v80, v69
	v_mov_b32_e32 v80, v194
	v_fmac_f32_e32 v139, v82, v38
	v_fmac_f32_e32 v158, v82, v54
	v_fmac_f32_e32 v120, v82, v22
	v_mul_f32_e32 v15, v157, v157
	v_fmac_f32_e32 v15, v14, v14
	v_fmac_f32_e32 v15, v138, v138
	v_fmac_f32_e32 v15, v118, v118
	v_mul_f32_e32 v85, v158, v158
	s_waitcnt vmcnt(0)
	v_fmac_f32_e32 v80, v82, v70
	v_mov_b32_e32 v121, v195
	s_nop 0
	v_mov_b32_e32 v145, v196
	v_mov_b32_e32 v166, v197
	v_mov_b32_e32 v82, v212
	v_add_co_u32_e32 v6, vcc, s4, v0
	s_movk_i32 s4, 0x6000
	s_nop 0
	v_addc_co_u32_e32 v7, vcc, 0, v1, vcc
	v_add_co_u32_e32 v126, vcc, s90, v0
	v_fmac_f32_e32 v85, v80, v80
	s_nop 0
	v_addc_co_u32_e32 v127, vcc, 0, v1, vcc
	v_add_co_u32_e32 v150, vcc, s86, v0
	v_fmac_f32_e32 v85, v139, v139
	s_nop 0
	v_addc_co_u32_e32 v151, vcc, 0, v1, vcc
	v_add_co_u32_e32 v160, vcc, s89, v0
	v_fmac_f32_e32 v85, v120, v120
	s_nop 0
	v_addc_co_u32_e32 v161, vcc, 0, v1, vcc
	v_add_co_u32_e32 v152, vcc, s87, v0
	v_mov_b32_e32 v170, v213
	v_mov_b32_e32 v149, v214
	v_addc_co_u32_e32 v153, vcc, 0, v1, vcc
	v_add_co_u32_e32 v162, vcc, s88, v0
	s_waitcnt vmcnt(0)
	v_fmac_f32_e32 v121, v84, v23
	v_addc_co_u32_e32 v163, vcc, 0, v1, vcc
	v_fmac_f32_e32 v82, v84, v71
	v_fmac_f32_e32 v166, v84, v55
	v_fmac_f32_e32 v145, v84, v39
	v_mov_b32_e32 v84, v215
	v_mov_b32_e32 v123, v216
	v_add_co_u32_e32 v164, vcc, s91, v0
	v_mul_f32_e32 v89, v166, v166
	s_nop 0
	v_addc_co_u32_e32 v165, vcc, 0, v1, vcc
	v_fmac_f32_e32 v89, v82, v82
	v_fmac_f32_e32 v89, v145, v145
	v_fmac_f32_e32 v89, v121, v121
	v_fmac_f32_e32 v170, v86, v56
	v_fmac_f32_e32 v149, v86, v40
	v_mul_f32_e32 v93, v170, v170
	s_waitcnt vmcnt(0)
	v_fmac_f32_e32 v84, v86, v72
	v_fmac_f32_e32 v123, v86, v24
	v_mov_b32_e32 v122, v217
	s_nop 0
	v_mov_b32_e32 v151, v218
	s_nop 0
	v_mov_b32_e32 v171, v219
	v_mov_b32_e32 v86, v220
	v_add_co_u32_e32 v6, vcc, s4, v0
	v_mov_b32_e32 v124, v221
	v_mov_b32_e32 v152, v222
	v_mov_b32_e32 v172, v223
	v_addc_co_u32_e32 v7, vcc, 0, v1, vcc
	s_mov_b32 s4, 0x1f000
	v_fmac_f32_e32 v93, v84, v84
	v_fmac_f32_e32 v93, v149, v149
	v_fmac_f32_e32 v93, v123, v123
	s_waitcnt vmcnt(0)
	v_fmac_f32_e32 v122, v88, v25
	v_fmac_f32_e32 v151, v88, v41
	v_fmac_f32_e32 v171, v88, v57
	v_fmac_f32_e32 v86, v88, v73
	v_mov_b32_e32 v88, v224
	v_fmac_f32_e32 v152, v90, v42
	v_fmac_f32_e32 v172, v90, v58
	v_fmac_f32_e32 v124, v90, v26
	v_mul_f32_e32 v87, v171, v171
	v_fmac_f32_e32 v87, v86, v86
	v_fmac_f32_e32 v87, v151, v151
	v_fmac_f32_e32 v87, v122, v122
	v_mul_f32_e32 v91, v172, v172
	s_waitcnt vmcnt(0)
	v_fmac_f32_e32 v88, v90, v74
	v_mov_b32_e32 v125, v225
	v_mov_b32_e32 v154, v226
	v_mov_b32_e32 v173, v227
	v_mov_b32_e32 v90, v229
	v_add_co_u32_e32 v160, vcc, s92, v0
	v_fmac_f32_e32 v91, v88, v88
	s_nop 0
	v_addc_co_u32_e32 v161, vcc, 0, v1, vcc
	v_add_co_u32_e32 v162, vcc, s96, v0
	v_fmac_f32_e32 v91, v152, v152
	s_nop 0
	v_addc_co_u32_e32 v163, vcc, 0, v1, vcc
	v_add_co_u32_e32 v168, vcc, s93, v0
	v_fmac_f32_e32 v91, v124, v124
	s_nop 0
	v_addc_co_u32_e32 v169, vcc, 0, v1, vcc
	v_add_co_u32_e32 v178, vcc, s95, v0
	v_mov_b32_e32 v174, v230
	s_nop 0
	v_addc_co_u32_e32 v179, vcc, 0, v1, vcc
	v_add_co_u32_e32 v176, vcc, s94, v0
	v_mov_b32_e32 v164, v231
	s_nop 0
	v_addc_co_u32_e32 v177, vcc, 0, v1, vcc
	v_add_co_u32_e32 v180, vcc, s4, v0
	s_mov_b64 s[4:5], 0x80
	s_nop 0
	v_addc_co_u32_e32 v181, vcc, 0, v1, vcc
	v_mov_b32_e32 v127, v232
	s_waitcnt vmcnt(0)
	v_fmac_f32_e32 v125, v92, v27
	v_fmac_f32_e32 v154, v92, v43
	v_fmac_f32_e32 v173, v92, v59
	v_fmac_f32_e32 v90, v92, v75
	v_mov_b32_e32 v92, v233
	v_mul_f32_e32 v95, v173, v173
	v_fmac_f32_e32 v95, v90, v90
	v_fmac_f32_e32 v95, v154, v154
	v_fmac_f32_e32 v95, v125, v125
	v_fmac_f32_e32 v174, v94, v60
	v_mul_f32_e32 v97, v174, v174
	v_fmac_f32_e32 v164, v94, v44
	v_fmac_f32_e32 v127, v94, v28
	s_waitcnt vmcnt(0)
	v_fmac_f32_e32 v92, v94, v76
	v_mov_b32_e32 v126, v234
	v_mov_b32_e32 v167, v235
	v_mov_b32_e32 v175, v236
	v_mov_b32_e32 v94, v237
	v_add_co_u32_e32 v160, vcc, s97, v0
	v_mov_b32_e32 v128, v238
	v_mov_b32_e32 v168, v239
	v_mov_b32_e32 v176, v240
	v_addc_co_u32_e32 v161, vcc, 0, v1, vcc
	v_fmac_f32_e32 v97, v92, v92
	v_fmac_f32_e32 v97, v164, v164
	v_fmac_f32_e32 v97, v127, v127
	s_waitcnt vmcnt(0)
	v_fmac_f32_e32 v126, v96, v29
	v_fmac_f32_e32 v167, v96, v45
	v_fmac_f32_e32 v175, v96, v61
	v_fmac_f32_e32 v94, v96, v77
	v_mov_b32_e32 v96, v241
	v_fmac_f32_e32 v168, v129, v46
	v_fmac_f32_e32 v176, v129, v62
	v_fmac_f32_e32 v128, v129, v30
	v_mul_f32_e32 v6, v175, v175
	v_fmac_f32_e32 v6, v94, v94
	v_fmac_f32_e32 v6, v167, v167
	v_fmac_f32_e32 v6, v126, v126
	v_mul_f32_e32 v7, v176, v176
	s_waitcnt vmcnt(0)
	v_fmac_f32_e32 v96, v129, v78
	v_mov_b32_e32 v129, v242
	v_mov_b32_e32 v169, v243
	v_mov_b32_e32 v177, v246
	s_nop 0
	v_mov_b32_e32 v178, v247
	v_fmac_f32_e32 v7, v96, v96
	v_fmac_f32_e32 v7, v168, v168
	v_fmac_f32_e32 v7, v128, v128
	s_waitcnt vmcnt(0)
	v_fmac_f32_e32 v129, v134, v31
	v_fmac_f32_e32 v169, v134, v47
	v_fmac_f32_e32 v177, v134, v63
	v_fmac_f32_e32 v178, v134, v79
	s_nop 1
	v_mov_b32_dpp v134, v13 quad_perm:[1,0,3,2] row_mask:0xf bank_mask:0xf
	v_mul_f32_e32 v165, v177, v177
	v_fmac_f32_e32 v165, v178, v178
	v_fmac_f32_e32 v165, v169, v169
	v_fmac_f32_e32 v165, v129, v129
	s_waitcnt lgkmcnt(0)
	v_add_f32_e32 v13, v13, v134
	s_nop 1
	v_mov_b32_dpp v134, v13 quad_perm:[2,3,0,1] row_mask:0xf bank_mask:0xf
	s_waitcnt lgkmcnt(0)
	v_add_f32_e32 v13, v13, v134
	s_nop 1
	v_mov_b32_dpp v134, v13 row_half_mirror row_mask:0xf bank_mask:0xf
	s_waitcnt lgkmcnt(0)
	v_add_f32_e32 v13, v13, v134
	s_nop 1
	v_mov_b32_dpp v134, v13 row_mirror row_mask:0xf bank_mask:0xf
	s_waitcnt lgkmcnt(0)
	v_add_f32_e32 v13, v13, v134
	v_mov_b32_e32 v247, v13
	v_mov_b32_e32 v134, v13
	s_nop 1
	v_permlane16_swap_b32_e32 v247, v134
	v_cndmask_b32_e64 v134, v134, v247, s[100:101]
	s_waitcnt lgkmcnt(0)
	v_add_f32_e32 v13, v13, v134
	v_fmamk_f32 v13, v13, 0x3c000000, v206
	v_rsq_f32_e32 v13, v13
	s_nop 0
	v_mul_f32_e32 v134, 0x3f24fd5c, v13
	s_nop 1
	v_mov_b32_dpp v13, v11 quad_perm:[1,0,3,2] row_mask:0xf bank_mask:0xf
	v_mul_f32_e32 v140, v134, v140
	v_mul_f32_e32 v130, v134, v130
	v_mul_f32_e32 v114, v134, v114
	s_waitcnt lgkmcnt(0)
	v_add_f32_e32 v11, v11, v13
	s_nop 1
	v_mov_b32_dpp v13, v11 quad_perm:[2,3,0,1] row_mask:0xf bank_mask:0xf
	s_waitcnt lgkmcnt(0)
	v_add_f32_e32 v11, v11, v13
	s_nop 1
	v_mov_b32_dpp v13, v11 row_half_mirror row_mask:0xf bank_mask:0xf
	s_waitcnt lgkmcnt(0)
	v_add_f32_e32 v11, v11, v13
	s_nop 1
	v_mov_b32_dpp v13, v11 row_mirror row_mask:0xf bank_mask:0xf
	s_waitcnt lgkmcnt(0)
	v_add_f32_e32 v11, v11, v13
	v_mov_b32_e32 v247, v11
	v_mov_b32_e32 v13, v11
	s_nop 1
	v_permlane16_swap_b32_e32 v247, v13
	v_cndmask_b32_e64 v13, v13, v247, s[100:101]
	s_waitcnt lgkmcnt(0)
	v_add_f32_e32 v11, v11, v13
	v_fmamk_f32 v11, v11, 0x3c000000, v206
	v_rsq_f32_e32 v11, v11
	s_nop 0
	v_mul_f32_e32 v135, 0x3f24fd5c, v11
	s_nop 1
	v_mov_b32_dpp v11, v2 quad_perm:[1,0,3,2] row_mask:0xf bank_mask:0xf
	v_mul_f32_e32 v8, v135, v8
	s_waitcnt lgkmcnt(0)
	v_add_f32_e32 v2, v2, v11
	s_nop 1
	v_mov_b32_dpp v11, v2 quad_perm:[2,3,0,1] row_mask:0xf bank_mask:0xf
	s_waitcnt lgkmcnt(0)
	v_add_f32_e32 v2, v2, v11
	s_nop 1
	v_mov_b32_dpp v11, v2 row_half_mirror row_mask:0xf bank_mask:0xf
	s_waitcnt lgkmcnt(0)
	v_add_f32_e32 v2, v2, v11
	s_nop 1
	v_mov_b32_dpp v11, v2 row_mirror row_mask:0xf bank_mask:0xf
	s_waitcnt lgkmcnt(0)
	v_add_f32_e32 v2, v2, v11
	v_mov_b32_e32 v247, v2
	v_mov_b32_e32 v11, v2
	s_nop 1
	v_permlane16_swap_b32_e32 v247, v11
	v_cndmask_b32_e64 v11, v11, v247, s[100:101]
	s_waitcnt lgkmcnt(0)
	v_add_f32_e32 v2, v2, v11
	v_fmamk_f32 v2, v2, 0x3c000000, v206
	v_rsq_f32_e32 v2, v2
	s_nop 0
	v_mul_f32_e32 v137, 0x3f24fd5c, v2
	s_nop 1
	v_mov_b32_dpp v2, v81 quad_perm:[1,0,3,2] row_mask:0xf bank_mask:0xf
	s_waitcnt lgkmcnt(0)
	v_add_f32_e32 v2, v81, v2
	s_nop 1
	v_mov_b32_dpp v11, v2 quad_perm:[2,3,0,1] row_mask:0xf bank_mask:0xf
	s_waitcnt lgkmcnt(0)
	v_add_f32_e32 v2, v2, v11
	s_nop 1
	v_mov_b32_dpp v11, v2 row_half_mirror row_mask:0xf bank_mask:0xf
	s_waitcnt lgkmcnt(0)
	v_add_f32_e32 v2, v2, v11
	s_nop 1
	v_mov_b32_dpp v11, v2 row_mirror row_mask:0xf bank_mask:0xf
	s_waitcnt lgkmcnt(0)
	v_add_f32_e32 v2, v2, v11
	v_mov_b32_e32 v247, v2
	v_mov_b32_e32 v11, v2
	s_nop 1
	v_permlane16_swap_b32_e32 v247, v11
	v_cndmask_b32_e64 v11, v11, v247, s[100:101]
	s_waitcnt lgkmcnt(0)
	v_add_f32_e32 v2, v2, v11
	v_fmamk_f32 v2, v2, 0x3c000000, v206
	v_rsq_f32_e32 v2, v2
	s_nop 0
	v_mul_f32_e32 v141, 0x3f24fd5c, v2
	s_nop 1
	v_mov_b32_dpp v2, v83 quad_perm:[1,0,3,2] row_mask:0xf bank_mask:0xf
	v_mul_f32_e32 v10, v141, v10
	s_waitcnt lgkmcnt(0)
	v_add_f32_e32 v2, v83, v2
	s_nop 1
	v_mov_b32_dpp v11, v2 quad_perm:[2,3,0,1] row_mask:0xf bank_mask:0xf
	s_waitcnt lgkmcnt(0)
	v_add_f32_e32 v2, v2, v11
	s_nop 1
	v_mov_b32_dpp v11, v2 row_half_mirror row_mask:0xf bank_mask:0xf
	s_waitcnt lgkmcnt(0)
	v_add_f32_e32 v2, v2, v11
	s_nop 1
	v_mov_b32_dpp v11, v2 row_mirror row_mask:0xf bank_mask:0xf
	s_waitcnt lgkmcnt(0)
	v_add_f32_e32 v2, v2, v11
	v_mov_b32_e32 v247, v2
	v_mov_b32_e32 v11, v2
	s_nop 1
	v_permlane16_swap_b32_e32 v247, v11
	v_cndmask_b32_e64 v11, v11, v247, s[100:101]
	s_waitcnt lgkmcnt(0)
	v_add_f32_e32 v2, v2, v11
	v_fmamk_f32 v2, v2, 0x3c000000, v206
	v_rsq_f32_e32 v2, v2
	s_nop 0
	v_mul_f32_e32 v144, 0x3f24fd5c, v2
	s_nop 1
	v_mov_b32_dpp v2, v15 quad_perm:[1,0,3,2] row_mask:0xf bank_mask:0xf
	v_mul_f32_e32 v12, v144, v12
	s_waitcnt lgkmcnt(0)
	v_add_f32_e32 v2, v15, v2
	s_nop 1
	v_mov_b32_dpp v11, v2 quad_perm:[2,3,0,1] row_mask:0xf bank_mask:0xf
	s_waitcnt lgkmcnt(0)
	v_add_f32_e32 v2, v2, v11
	s_nop 1
	v_mov_b32_dpp v11, v2 row_half_mirror row_mask:0xf bank_mask:0xf
	s_waitcnt lgkmcnt(0)
	v_add_f32_e32 v2, v2, v11
	s_nop 1
	v_mov_b32_dpp v11, v2 row_mirror row_mask:0xf bank_mask:0xf
	s_waitcnt lgkmcnt(0)
	v_add_f32_e32 v2, v2, v11
	v_mov_b32_e32 v247, v2
	v_mov_b32_e32 v11, v2
	s_nop 1
	v_permlane16_swap_b32_e32 v247, v11
	v_cndmask_b32_e64 v11, v11, v247, s[100:101]
	s_waitcnt lgkmcnt(0)
	v_add_f32_e32 v2, v2, v11
	v_fmamk_f32 v2, v2, 0x3c000000, v206
	v_rsq_f32_e32 v2, v2
	s_nop 0
	v_mul_f32_e32 v147, 0x3f24fd5c, v2
	s_nop 1
	v_mov_b32_dpp v2, v85 quad_perm:[1,0,3,2] row_mask:0xf bank_mask:0xf
	v_mul_f32_e32 v14, v147, v14
	s_waitcnt lgkmcnt(0)
	v_add_f32_e32 v2, v85, v2
	s_nop 1
	v_mov_b32_dpp v11, v2 quad_perm:[2,3,0,1] row_mask:0xf bank_mask:0xf
	s_waitcnt lgkmcnt(0)
	v_add_f32_e32 v2, v2, v11
	s_nop 1
	v_mov_b32_dpp v11, v2 row_half_mirror row_mask:0xf bank_mask:0xf
	s_waitcnt lgkmcnt(0)
	v_add_f32_e32 v2, v2, v11
	s_nop 1
	v_mov_b32_dpp v11, v2 row_mirror row_mask:0xf bank_mask:0xf
	s_waitcnt lgkmcnt(0)
	v_add_f32_e32 v2, v2, v11
	v_mov_b32_e32 v247, v2
	v_mov_b32_e32 v11, v2
	s_nop 1
	v_permlane16_swap_b32_e32 v247, v11
	v_cndmask_b32_e64 v11, v11, v247, s[100:101]
	s_waitcnt lgkmcnt(0)
	v_add_f32_e32 v2, v2, v11
	v_fmamk_f32 v2, v2, 0x3c000000, v206
	v_rsq_f32_e32 v2, v2
	s_nop 0
	v_mul_f32_e32 v148, 0x3f24fd5c, v2
	s_nop 1
	v_mov_b32_dpp v2, v89 quad_perm:[1,0,3,2] row_mask:0xf bank_mask:0xf
	v_mul_f32_e32 v80, v148, v80
	s_waitcnt lgkmcnt(0)
	v_add_f32_e32 v2, v89, v2
	s_nop 1
	v_mov_b32_dpp v11, v2 quad_perm:[2,3,0,1] row_mask:0xf bank_mask:0xf
	s_waitcnt lgkmcnt(0)
	v_add_f32_e32 v2, v2, v11
	s_nop 1
	v_mov_b32_dpp v11, v2 row_half_mirror row_mask:0xf bank_mask:0xf
	s_waitcnt lgkmcnt(0)
	v_add_f32_e32 v2, v2, v11
	s_nop 1
	v_mov_b32_dpp v11, v2 row_mirror row_mask:0xf bank_mask:0xf
	s_waitcnt lgkmcnt(0)
	v_add_f32_e32 v2, v2, v11
	v_mov_b32_e32 v247, v2
	v_mov_b32_e32 v11, v2
	s_nop 1
	v_permlane16_swap_b32_e32 v247, v11
	v_cndmask_b32_e64 v11, v11, v247, s[100:101]
	s_waitcnt lgkmcnt(0)
	v_add_f32_e32 v2, v2, v11
	v_fmamk_f32 v2, v2, 0x3c000000, v206
	v_rsq_f32_e32 v2, v2
	s_nop 0
	v_mul_f32_e32 v150, 0x3f24fd5c, v2
	s_nop 1
	v_mov_b32_dpp v2, v93 quad_perm:[1,0,3,2] row_mask:0xf bank_mask:0xf
	v_mul_f32_e32 v82, v150, v82
	s_waitcnt lgkmcnt(0)
	v_add_f32_e32 v2, v93, v2
	s_nop 1
	v_mov_b32_dpp v11, v2 quad_perm:[2,3,0,1] row_mask:0xf bank_mask:0xf
	s_waitcnt lgkmcnt(0)
	v_add_f32_e32 v2, v2, v11
	s_nop 1
	v_mov_b32_dpp v11, v2 row_half_mirror row_mask:0xf bank_mask:0xf
	s_waitcnt lgkmcnt(0)
	v_add_f32_e32 v2, v2, v11
	s_nop 1
	v_mov_b32_dpp v11, v2 row_mirror row_mask:0xf bank_mask:0xf
	s_waitcnt lgkmcnt(0)
	v_add_f32_e32 v2, v2, v11
	v_mov_b32_e32 v247, v2
	v_mov_b32_e32 v11, v2
	s_nop 1
	v_permlane16_swap_b32_e32 v247, v11
	v_cndmask_b32_e64 v11, v11, v247, s[100:101]
	s_waitcnt lgkmcnt(0)
	v_add_f32_e32 v2, v2, v11
	v_fmamk_f32 v2, v2, 0x3c000000, v206
	v_rsq_f32_e32 v2, v2
	s_nop 0
	v_mul_f32_e32 v153, 0x3f24fd5c, v2
	s_nop 1
	v_mov_b32_dpp v2, v87 quad_perm:[1,0,3,2] row_mask:0xf bank_mask:0xf
	v_mul_f32_e32 v84, v153, v84
	s_waitcnt lgkmcnt(0)
	v_add_f32_e32 v2, v87, v2
	s_nop 1
	v_mov_b32_dpp v11, v2 quad_perm:[2,3,0,1] row_mask:0xf bank_mask:0xf
	s_waitcnt lgkmcnt(0)
	v_add_f32_e32 v2, v2, v11
	s_nop 1
	v_mov_b32_dpp v11, v2 row_half_mirror row_mask:0xf bank_mask:0xf
	s_waitcnt lgkmcnt(0)
	v_add_f32_e32 v2, v2, v11
	s_nop 1
	v_mov_b32_dpp v11, v2 row_mirror row_mask:0xf bank_mask:0xf
	s_waitcnt lgkmcnt(0)
	v_add_f32_e32 v2, v2, v11
	v_mov_b32_e32 v247, v2
	v_mov_b32_e32 v11, v2
	s_nop 1
	v_permlane16_swap_b32_e32 v247, v11
	v_cndmask_b32_e64 v11, v11, v247, s[100:101]
	s_waitcnt lgkmcnt(0)
	v_add_f32_e32 v2, v2, v11
	v_fmamk_f32 v2, v2, 0x3c000000, v206
	v_rsq_f32_e32 v2, v2
	s_nop 0
	v_mul_f32_e32 v156, 0x3f24fd5c, v2
	s_nop 1
	v_mov_b32_dpp v2, v91 quad_perm:[1,0,3,2] row_mask:0xf bank_mask:0xf
	v_mul_f32_e32 v86, v156, v86
	s_waitcnt lgkmcnt(0)
	v_add_f32_e32 v2, v91, v2
	s_nop 1
	v_mov_b32_dpp v11, v2 quad_perm:[2,3,0,1] row_mask:0xf bank_mask:0xf
	s_waitcnt lgkmcnt(0)
	v_add_f32_e32 v2, v2, v11
	s_nop 1
	v_mov_b32_dpp v11, v2 row_half_mirror row_mask:0xf bank_mask:0xf
	s_waitcnt lgkmcnt(0)
	v_add_f32_e32 v2, v2, v11
	s_nop 1
	v_mov_b32_dpp v11, v2 row_mirror row_mask:0xf bank_mask:0xf
	s_waitcnt lgkmcnt(0)
	v_add_f32_e32 v2, v2, v11
	v_mov_b32_e32 v247, v2
	v_mov_b32_e32 v11, v2
	s_nop 1
	v_permlane16_swap_b32_e32 v247, v11
	v_cndmask_b32_e64 v11, v11, v247, s[100:101]
	s_waitcnt lgkmcnt(0)
	v_add_f32_e32 v2, v2, v11
	v_fmamk_f32 v2, v2, 0x3c000000, v206
	v_rsq_f32_e32 v2, v2
	s_nop 0
	v_mul_f32_e32 v159, 0x3f24fd5c, v2
	s_nop 1
	v_mov_b32_dpp v2, v95 quad_perm:[1,0,3,2] row_mask:0xf bank_mask:0xf
	v_mul_f32_e32 v88, v159, v88
	s_waitcnt lgkmcnt(0)
	v_add_f32_e32 v2, v95, v2
	s_nop 1
	v_mov_b32_dpp v11, v2 quad_perm:[2,3,0,1] row_mask:0xf bank_mask:0xf
	s_waitcnt lgkmcnt(0)
	v_add_f32_e32 v2, v2, v11
	s_nop 1
	v_mov_b32_dpp v11, v2 row_half_mirror row_mask:0xf bank_mask:0xf
	s_waitcnt lgkmcnt(0)
	v_add_f32_e32 v2, v2, v11
	s_nop 1
	v_mov_b32_dpp v11, v2 row_mirror row_mask:0xf bank_mask:0xf
	s_waitcnt lgkmcnt(0)
	v_add_f32_e32 v2, v2, v11
	v_mov_b32_e32 v247, v2
	v_mov_b32_e32 v11, v2
	s_nop 1
	v_permlane16_swap_b32_e32 v247, v11
	v_cndmask_b32_e64 v11, v11, v247, s[100:101]
	s_waitcnt lgkmcnt(0)
	v_add_f32_e32 v2, v2, v11
	v_fmamk_f32 v2, v2, 0x3c000000, v206
	v_rsq_f32_e32 v2, v2
	s_nop 0
	v_mul_f32_e32 v160, 0x3f24fd5c, v2
	s_nop 1
	v_mov_b32_dpp v2, v97 quad_perm:[1,0,3,2] row_mask:0xf bank_mask:0xf
	v_mul_f32_e32 v90, v160, v90
	s_waitcnt lgkmcnt(0)
	v_add_f32_e32 v2, v97, v2
	s_nop 1
	v_mov_b32_dpp v11, v2 quad_perm:[2,3,0,1] row_mask:0xf bank_mask:0xf
	s_waitcnt lgkmcnt(0)
	v_add_f32_e32 v2, v2, v11
	s_nop 1
	v_mov_b32_dpp v11, v2 row_half_mirror row_mask:0xf bank_mask:0xf
	s_waitcnt lgkmcnt(0)
	v_add_f32_e32 v2, v2, v11
	s_nop 1
	v_mov_b32_dpp v11, v2 row_mirror row_mask:0xf bank_mask:0xf
	s_waitcnt lgkmcnt(0)
	v_add_f32_e32 v2, v2, v11
	v_mov_b32_e32 v247, v2
	v_mov_b32_e32 v11, v2
	s_nop 1
	v_permlane16_swap_b32_e32 v247, v11
	v_cndmask_b32_e64 v11, v11, v247, s[100:101]
	s_waitcnt lgkmcnt(0)
	v_add_f32_e32 v2, v2, v11
	v_fmamk_f32 v2, v2, 0x3c000000, v206
	v_rsq_f32_e32 v2, v2
	v_and_b32_e32 v11, 31, v4
	v_lshlrev_b32_e32 v179, 2, v11
	global_load_dword v182, v179, s[6:7]
	v_mul_f32_e32 v161, 0x3f24fd5c, v2
	s_nop 1
	v_mov_b32_dpp v2, v6 quad_perm:[1,0,3,2] row_mask:0xf bank_mask:0xf
	v_mul_f32_e32 v92, v161, v92
	s_waitcnt lgkmcnt(0)
	v_add_f32_e32 v2, v6, v2
	s_nop 1
	v_mov_b32_dpp v6, v2 quad_perm:[2,3,0,1] row_mask:0xf bank_mask:0xf
	s_waitcnt lgkmcnt(0)
	v_add_f32_e32 v2, v2, v6
	s_nop 1
	v_mov_b32_dpp v6, v2 row_half_mirror row_mask:0xf bank_mask:0xf
	s_waitcnt lgkmcnt(0)
	v_add_f32_e32 v2, v2, v6
	s_nop 1
	v_mov_b32_dpp v6, v2 row_mirror row_mask:0xf bank_mask:0xf
	s_waitcnt lgkmcnt(0)
	v_add_f32_e32 v2, v2, v6
	v_mov_b32_e32 v247, v2
	v_mov_b32_e32 v6, v2
	s_nop 1
	v_permlane16_swap_b32_e32 v247, v6
	v_cndmask_b32_e64 v6, v6, v247, s[100:101]
	s_waitcnt lgkmcnt(0)
	v_add_f32_e32 v2, v2, v6
	v_fmamk_f32 v2, v2, 0x3c000000, v206
	v_rsq_f32_e32 v2, v2
	s_waitcnt vmcnt(0)
	v_mul_f32_e32 v8, v182, v8
	v_mul_f32_e32 v162, 0x3f24fd5c, v2
	s_nop 1
	v_mov_b32_dpp v2, v7 quad_perm:[1,0,3,2] row_mask:0xf bank_mask:0xf
	v_mul_f32_e32 v10, v182, v10
	v_mul_f32_e32 v12, v182, v12
	v_mul_f32_e32 v14, v182, v14
	v_mul_f32_e32 v80, v182, v80
	s_waitcnt lgkmcnt(0)
	v_add_f32_e32 v2, v7, v2
	s_nop 1
	v_mov_b32_dpp v6, v2 quad_perm:[2,3,0,1] row_mask:0xf bank_mask:0xf
	v_mul_f32_e32 v82, v182, v82
	v_mul_f32_e32 v84, v182, v84
	v_mul_f32_e32 v86, v182, v86
	v_mul_f32_e32 v88, v182, v88
	s_waitcnt lgkmcnt(0)
	v_add_f32_e32 v2, v2, v6
	s_nop 1
	v_mov_b32_dpp v6, v2 row_half_mirror row_mask:0xf bank_mask:0xf
	v_mul_f32_e32 v90, v182, v90
	v_mul_f32_e32 v92, v182, v92
	v_mul_f32_e32 v94, v162, v94
	v_mul_f32_e32 v94, v182, v94
	s_waitcnt lgkmcnt(0)
	v_add_f32_e32 v2, v2, v6
	s_nop 1
	v_mov_b32_dpp v6, v2 row_mirror row_mask:0xf bank_mask:0xf
	s_waitcnt lgkmcnt(0)
	v_add_f32_e32 v2, v2, v6
	v_mov_b32_e32 v247, v2
	v_mov_b32_e32 v6, v2
	s_nop 1
	v_permlane16_swap_b32_e32 v247, v6
	v_cndmask_b32_e64 v6, v6, v247, s[100:101]
	s_waitcnt lgkmcnt(0)
	v_add_f32_e32 v2, v2, v6
	v_fmamk_f32 v2, v2, 0x3c000000, v206
	v_rsq_f32_e32 v2, v2
	s_nop 0
	v_mul_f32_e32 v163, 0x3f24fd5c, v2
	s_nop 1
	v_mov_b32_dpp v2, v165 quad_perm:[1,0,3,2] row_mask:0xf bank_mask:0xf
	v_mul_f32_e32 v96, v163, v96
	v_mul_f32_e32 v96, v182, v96
	s_waitcnt lgkmcnt(0)
	v_add_f32_e32 v2, v165, v2
	s_nop 1
	v_mov_b32_dpp v6, v2 quad_perm:[2,3,0,1] row_mask:0xf bank_mask:0xf
	s_waitcnt lgkmcnt(0)
	v_add_f32_e32 v2, v2, v6
	s_nop 1
	v_mov_b32_dpp v6, v2 row_half_mirror row_mask:0xf bank_mask:0xf
	s_waitcnt lgkmcnt(0)
	v_add_f32_e32 v2, v2, v6
	s_nop 1
	v_mov_b32_dpp v6, v2 row_mirror row_mask:0xf bank_mask:0xf
	s_waitcnt lgkmcnt(0)
	v_add_f32_e32 v2, v2, v6
	v_mov_b32_e32 v247, v2
	v_mov_b32_e32 v6, v2
	s_nop 1
	v_permlane16_swap_b32_e32 v247, v6
	v_cndmask_b32_e64 v6, v6, v247, s[100:101]
	s_waitcnt lgkmcnt(0)
	v_add_f32_e32 v2, v2, v6
	v_fmamk_f32 v2, v2, 0x3c000000, v206
	v_rsq_f32_e32 v2, v2
	s_nop 0
	v_mul_f32_e32 v165, 0x3f24fd5c, v2
	v_lshlrev_b32_e32 v2, 1, v11
	v_lshl_add_u64 v[6:7], s[46:47], 0, v[2:3]
	v_mul_f32_e32 v2, v134, v5
	v_mul_f32_e32 v2, v182, v2
	v_bfe_u32 v5, v2, 16, 1
	v_add3_u32 v11, v2, v5, s30
	v_lshlrev_b32_e32 v2, 8, v4
	v_and_b32_e32 v2, 0x2000, v2
	v_lshl_add_u64 v[4:5], v[6:7], 0, v[2:3]
	global_store_short_d16_hi v[4:5], v11, off sc1
	v_bfe_u32 v11, v8, 16, 1
	v_add3_u32 v8, v8, v11, s30
	global_store_short_d16_hi v[4:5], v8, off offset:2048 sc1
	v_mul_f32_e32 v8, v137, v9
	v_mul_f32_e32 v8, v182, v8
	v_bfe_u32 v9, v8, 16, 1
	v_add3_u32 v11, v8, v9, s30
	v_or_b32_e32 v8, 0x1000, v2
	v_mov_b32_e32 v9, v3
	v_lshl_add_u64 v[180:181], v[6:7], 0, v[8:9]
	global_store_short_d16_hi v[180:181], v11, off sc1
	v_bfe_u32 v11, v10, 16, 1
	v_add3_u32 v13, v10, v11, s30
	v_or_b32_e32 v10, 0x1800, v2
	v_mov_b32_e32 v11, v3
	v_lshl_add_u64 v[180:181], v[6:7], 0, v[10:11]
	global_store_short_d16_hi v[180:181], v13, off sc1
	v_bfe_u32 v13, v12, 16, 1
	v_add3_u32 v15, v12, v13, s30
	v_or_b32_e32 v12, 0x4000, v2
	v_mov_b32_e32 v13, v3
	v_lshl_add_u64 v[180:181], v[6:7], 0, v[12:13]
	global_store_short_d16_hi v[180:181], v15, off sc1
	v_bfe_u32 v15, v14, 16, 1
	v_add3_u32 v81, v14, v15, s30
	v_or_b32_e32 v14, 0x4800, v2
	v_mov_b32_e32 v15, v3
	v_lshl_add_u64 v[180:181], v[6:7], 0, v[14:15]
	global_store_short_d16_hi v[180:181], v81, off sc1
	v_bfe_u32 v81, v80, 16, 1
	v_add3_u32 v83, v80, v81, s30
	v_or_b32_e32 v80, 0x5000, v2
	v_mov_b32_e32 v81, v3
	v_lshl_add_u64 v[180:181], v[6:7], 0, v[80:81]
	global_store_short_d16_hi v[180:181], v83, off sc1
	v_bfe_u32 v83, v82, 16, 1
	v_add3_u32 v85, v82, v83, s30
	v_or_b32_e32 v82, 0x5800, v2
	v_mov_b32_e32 v83, v3
	v_lshl_add_u64 v[180:181], v[6:7], 0, v[82:83]
	global_store_short_d16_hi v[180:181], v85, off sc1
	v_bfe_u32 v85, v84, 16, 1
	v_add3_u32 v87, v84, v85, s30
	v_or_b32_e32 v84, 0x8000, v2
	v_mov_b32_e32 v85, v3
	v_lshl_add_u64 v[180:181], v[6:7], 0, v[84:85]
	global_store_short_d16_hi v[180:181], v87, off sc1
	v_bfe_u32 v87, v86, 16, 1
	v_add3_u32 v89, v86, v87, s30
	v_or_b32_e32 v86, 0x8800, v2
	v_mov_b32_e32 v87, v3
	v_lshl_add_u64 v[180:181], v[6:7], 0, v[86:87]
	global_store_short_d16_hi v[180:181], v89, off sc1
	v_bfe_u32 v89, v88, 16, 1
	v_add3_u32 v91, v88, v89, s30
	v_or_b32_e32 v88, 0x9000, v2
	v_mov_b32_e32 v89, v3
	v_lshl_add_u64 v[180:181], v[6:7], 0, v[88:89]
	global_store_short_d16_hi v[180:181], v91, off sc1
	v_bfe_u32 v91, v90, 16, 1
	v_add3_u32 v93, v90, v91, s30
	v_or_b32_e32 v90, 0x9800, v2
	v_mov_b32_e32 v91, v3
	v_lshl_add_u64 v[180:181], v[6:7], 0, v[90:91]
	global_store_short_d16_hi v[180:181], v93, off sc1
	v_bfe_u32 v93, v92, 16, 1
	v_add3_u32 v95, v92, v93, s30
	v_or_b32_e32 v92, 0xc000, v2
	v_mov_b32_e32 v93, v3
	v_lshl_add_u64 v[180:181], v[6:7], 0, v[92:93]
	global_store_short_d16_hi v[180:181], v95, off sc1
	v_bfe_u32 v95, v94, 16, 1
	v_add3_u32 v97, v94, v95, s30
	v_or_b32_e32 v94, 0xc800, v2
	v_mov_b32_e32 v95, v3
	v_lshl_add_u64 v[180:181], v[6:7], 0, v[94:95]
	global_store_short_d16_hi v[180:181], v97, off sc1
	v_bfe_u32 v97, v96, 16, 1
	v_add3_u32 v183, v96, v97, s30
	v_or_b32_e32 v96, 0xd000, v2
	v_mov_b32_e32 v97, v3
	v_mul_f32_e32 v178, v165, v178
	v_lshl_add_u64 v[180:181], v[6:7], 0, v[96:97]
	v_mul_f32_e32 v178, v182, v178
	global_store_short_d16_hi v[180:181], v183, off sc1
	v_bfe_u32 v180, v178, 16, 1
	v_or_b32_e32 v2, 0xd800, v2
	v_add3_u32 v178, v178, v180, s30
	v_lshl_add_u64 v[180:181], v[6:7], 0, v[2:3]
	global_store_short_d16_hi v[180:181], v178, off sc1
	global_load_dword v178, v179, s[6:7] offset:128
	v_lshl_add_u64 v[180:181], v[6:7], 0, 64
	s_waitcnt vmcnt(0)
	v_mul_f32_e32 v140, v178, v140
	v_bfe_u32 v182, v140, 16, 1
	v_add3_u32 v140, v140, v182, s30
	global_store_short_d16_hi v[4:5], v140, off offset:64 sc1
	v_mul_f32_e32 v140, v135, v142
	v_mul_f32_e32 v140, v178, v140
	v_bfe_u32 v142, v140, 16, 1
	v_add3_u32 v140, v140, v142, s30
	global_store_short_d16_hi v[4:5], v140, off offset:2112 sc1
	v_mul_f32_e32 v140, v137, v143
	v_mul_f32_e32 v140, v178, v140
	v_bfe_u32 v142, v140, 16, 1
	v_add3_u32 v140, v140, v142, s30
	v_lshl_add_u64 v[142:143], v[180:181], 0, v[8:9]
	global_store_short_d16_hi v[142:143], v140, off sc1
	v_mul_f32_e32 v140, v141, v146
	v_mul_f32_e32 v140, v178, v140
	v_bfe_u32 v142, v140, 16, 1
	v_add3_u32 v140, v140, v142, s30
	v_lshl_add_u64 v[142:143], v[180:181], 0, v[10:11]
	global_store_short_d16_hi v[142:143], v140, off sc1
	v_mul_f32_e32 v140, v144, v155
	v_mul_f32_e32 v140, v178, v140
	v_bfe_u32 v142, v140, 16, 1
	v_add3_u32 v140, v140, v142, s30
	v_lshl_add_u64 v[142:143], v[180:181], 0, v[12:13]
	global_store_short_d16_hi v[142:143], v140, off sc1
	v_mul_f32_e32 v140, v147, v157
	v_mul_f32_e32 v140, v178, v140
	v_bfe_u32 v142, v140, 16, 1
	v_add3_u32 v140, v140, v142, s30
	v_lshl_add_u64 v[142:143], v[180:181], 0, v[14:15]
	global_store_short_d16_hi v[142:143], v140, off sc1
	v_mul_f32_e32 v140, v148, v158
	v_mul_f32_e32 v140, v178, v140
	v_bfe_u32 v142, v140, 16, 1
	v_add3_u32 v140, v140, v142, s30
	v_lshl_add_u64 v[142:143], v[180:181], 0, v[80:81]
	global_store_short_d16_hi v[142:143], v140, off sc1
	v_mul_f32_e32 v140, v150, v166
	v_mul_f32_e32 v140, v178, v140
	v_bfe_u32 v142, v140, 16, 1
	v_add3_u32 v140, v140, v142, s30
	v_lshl_add_u64 v[142:143], v[180:181], 0, v[82:83]
	global_store_short_d16_hi v[142:143], v140, off sc1
	v_mul_f32_e32 v140, v153, v170
	v_mul_f32_e32 v140, v178, v140
	v_bfe_u32 v142, v140, 16, 1
	v_add3_u32 v140, v140, v142, s30
	v_lshl_add_u64 v[142:143], v[180:181], 0, v[84:85]
	global_store_short_d16_hi v[142:143], v140, off sc1
	v_mul_f32_e32 v140, v156, v171
	v_mul_f32_e32 v140, v178, v140
	v_bfe_u32 v142, v140, 16, 1
	v_add3_u32 v140, v140, v142, s30
	v_lshl_add_u64 v[142:143], v[180:181], 0, v[86:87]
	global_store_short_d16_hi v[142:143], v140, off sc1
	v_mul_f32_e32 v140, v159, v172
	v_mul_f32_e32 v140, v178, v140
	v_bfe_u32 v142, v140, 16, 1
	v_add3_u32 v140, v140, v142, s30
	v_lshl_add_u64 v[142:143], v[180:181], 0, v[88:89]
	global_store_short_d16_hi v[142:143], v140, off sc1
	v_mul_f32_e32 v140, v160, v173
	v_mul_f32_e32 v140, v178, v140
	v_bfe_u32 v142, v140, 16, 1
	v_add3_u32 v140, v140, v142, s30
	v_lshl_add_u64 v[142:143], v[180:181], 0, v[90:91]
	global_store_short_d16_hi v[142:143], v140, off sc1
	v_mul_f32_e32 v140, v161, v174
	v_mul_f32_e32 v140, v178, v140
	v_bfe_u32 v142, v140, 16, 1
	v_add3_u32 v140, v140, v142, s30
	v_lshl_add_u64 v[142:143], v[180:181], 0, v[92:93]
	global_store_short_d16_hi v[142:143], v140, off sc1
	v_mul_f32_e32 v140, v162, v175
	v_mul_f32_e32 v140, v178, v140
	v_bfe_u32 v142, v140, 16, 1
	v_add3_u32 v140, v140, v142, s30
	v_lshl_add_u64 v[142:143], v[180:181], 0, v[94:95]
	global_store_short_d16_hi v[142:143], v140, off sc1
	v_mul_f32_e32 v140, v163, v176
	v_mul_f32_e32 v140, v178, v140
	v_bfe_u32 v142, v140, 16, 1
	v_add3_u32 v140, v140, v142, s30
	v_lshl_add_u64 v[142:143], v[180:181], 0, v[96:97]
	global_store_short_d16_hi v[142:143], v140, off sc1
	v_mul_f32_e32 v140, v165, v177
	v_mul_f32_e32 v140, v178, v140
	v_bfe_u32 v142, v140, 16, 1
	v_add3_u32 v140, v140, v142, s30
	v_lshl_add_u64 v[142:143], v[180:181], 0, v[2:3]
	global_store_short_d16_hi v[142:143], v140, off sc1
	global_load_dword v140, v179, s[6:7] offset:256
	v_lshl_add_u64 v[142:143], v[6:7], 0, s[4:5]
	s_mov_b64 s[4:5], 0xc0
	v_lshl_add_u64 v[6:7], v[6:7], 0, s[4:5]
	s_mov_b64 s[4:5], 0
	s_waitcnt vmcnt(0)
	v_mul_f32_e32 v130, v140, v130
	v_bfe_u32 v146, v130, 16, 1
	v_add3_u32 v130, v130, v146, s30
	global_store_short_d16_hi v[4:5], v130, off offset:128 sc1
	v_mul_f32_e32 v130, v135, v131
	v_mul_f32_e32 v130, v140, v130
	v_bfe_u32 v131, v130, 16, 1
	v_add3_u32 v130, v130, v131, s30
	global_store_short_d16_hi v[4:5], v130, off offset:2176 sc1
	v_mul_f32_e32 v130, v137, v132
	v_mul_f32_e32 v130, v140, v130
	v_bfe_u32 v131, v130, 16, 1
	v_add3_u32 v132, v130, v131, s30
	v_lshl_add_u64 v[130:131], v[142:143], 0, v[8:9]
	global_store_short_d16_hi v[130:131], v132, off sc1
	v_mul_f32_e32 v130, v141, v133
	v_mul_f32_e32 v130, v140, v130
	v_bfe_u32 v131, v130, 16, 1
	v_add3_u32 v132, v130, v131, s30
	v_lshl_add_u64 v[130:131], v[142:143], 0, v[10:11]
	global_store_short_d16_hi v[130:131], v132, off sc1
	v_mul_f32_e32 v130, v144, v136
	v_mul_f32_e32 v130, v140, v130
	v_bfe_u32 v131, v130, 16, 1
	v_add3_u32 v132, v130, v131, s30
	v_lshl_add_u64 v[130:131], v[142:143], 0, v[12:13]
	global_store_short_d16_hi v[130:131], v132, off sc1
	v_mul_f32_e32 v130, v147, v138
	v_mul_f32_e32 v130, v140, v130
	v_bfe_u32 v131, v130, 16, 1
	v_add3_u32 v132, v130, v131, s30
	v_lshl_add_u64 v[130:131], v[142:143], 0, v[14:15]
	global_store_short_d16_hi v[130:131], v132, off sc1
	v_mul_f32_e32 v130, v148, v139
	v_mul_f32_e32 v130, v140, v130
	v_bfe_u32 v131, v130, 16, 1
	v_add3_u32 v132, v130, v131, s30
	v_lshl_add_u64 v[130:131], v[142:143], 0, v[80:81]
	global_store_short_d16_hi v[130:131], v132, off sc1
	v_mul_f32_e32 v130, v150, v145
	v_mul_f32_e32 v130, v140, v130
	v_bfe_u32 v131, v130, 16, 1
	v_add3_u32 v132, v130, v131, s30
	v_lshl_add_u64 v[130:131], v[142:143], 0, v[82:83]
	global_store_short_d16_hi v[130:131], v132, off sc1
	v_mul_f32_e32 v130, v153, v149
	v_mul_f32_e32 v130, v140, v130
	v_bfe_u32 v131, v130, 16, 1
	v_add3_u32 v132, v130, v131, s30
	v_lshl_add_u64 v[130:131], v[142:143], 0, v[84:85]
	global_store_short_d16_hi v[130:131], v132, off sc1
	v_mul_f32_e32 v130, v156, v151
	v_mul_f32_e32 v130, v140, v130
	v_bfe_u32 v131, v130, 16, 1
	v_add3_u32 v132, v130, v131, s30
	v_lshl_add_u64 v[130:131], v[142:143], 0, v[86:87]
	global_store_short_d16_hi v[130:131], v132, off sc1
	v_mul_f32_e32 v130, v159, v152
	v_mul_f32_e32 v130, v140, v130
	v_bfe_u32 v131, v130, 16, 1
	v_add3_u32 v132, v130, v131, s30
	v_lshl_add_u64 v[130:131], v[142:143], 0, v[88:89]
	global_store_short_d16_hi v[130:131], v132, off sc1
	v_mul_f32_e32 v130, v160, v154
	v_mul_f32_e32 v130, v140, v130
	v_bfe_u32 v131, v130, 16, 1
	v_add3_u32 v132, v130, v131, s30
	v_lshl_add_u64 v[130:131], v[142:143], 0, v[90:91]
	global_store_short_d16_hi v[130:131], v132, off sc1
	v_mul_f32_e32 v130, v161, v164
	v_mul_f32_e32 v130, v140, v130
	v_bfe_u32 v131, v130, 16, 1
	v_add3_u32 v132, v130, v131, s30
	v_lshl_add_u64 v[130:131], v[142:143], 0, v[92:93]
	global_store_short_d16_hi v[130:131], v132, off sc1
	v_mul_f32_e32 v130, v162, v167
	v_mul_f32_e32 v130, v140, v130
	v_bfe_u32 v131, v130, 16, 1
	v_add3_u32 v132, v130, v131, s30
	v_lshl_add_u64 v[130:131], v[142:143], 0, v[94:95]
	global_store_short_d16_hi v[130:131], v132, off sc1
	v_mul_f32_e32 v130, v163, v168
	v_mul_f32_e32 v130, v140, v130
	v_bfe_u32 v131, v130, 16, 1
	v_add3_u32 v132, v130, v131, s30
	v_lshl_add_u64 v[130:131], v[142:143], 0, v[96:97]
	global_store_short_d16_hi v[130:131], v132, off sc1
	v_mul_f32_e32 v130, v165, v169
	v_mul_f32_e32 v130, v140, v130
	v_bfe_u32 v131, v130, 16, 1
	v_add3_u32 v132, v130, v131, s30
	v_lshl_add_u64 v[130:131], v[142:143], 0, v[2:3]
	global_store_short_d16_hi v[130:131], v132, off sc1
	global_load_dword v130, v179, s[6:7] offset:384
	s_waitcnt vmcnt(0)
	v_mul_f32_e32 v114, v130, v114
	v_bfe_u32 v131, v114, 16, 1
	v_add3_u32 v114, v114, v131, s30
	global_store_short_d16_hi v[4:5], v114, off offset:192 sc1
	v_mul_f32_e32 v114, v135, v115
	v_mul_f32_e32 v114, v130, v114
	v_bfe_u32 v115, v114, 16, 1
	v_add3_u32 v114, v114, v115, s30
	global_store_short_d16_hi v[4:5], v114, off offset:2240 sc1
	v_mul_f32_e32 v4, v137, v116
	v_mul_f32_e32 v4, v130, v4
	v_bfe_u32 v5, v4, 16, 1
	v_add3_u32 v114, v4, v5, s30
	v_lshl_add_u64 v[4:5], v[6:7], 0, v[8:9]
	global_store_short_d16_hi v[4:5], v114, off sc1
	v_mul_f32_e32 v4, v141, v117
	v_mul_f32_e32 v4, v130, v4
	v_bfe_u32 v5, v4, 16, 1
	v_add3_u32 v8, v4, v5, s30
	v_lshl_add_u64 v[4:5], v[6:7], 0, v[10:11]
	global_store_short_d16_hi v[4:5], v8, off sc1
	v_mul_f32_e32 v4, v144, v119
	v_mul_f32_e32 v4, v130, v4
	v_bfe_u32 v5, v4, 16, 1
	v_add3_u32 v8, v4, v5, s30
	v_lshl_add_u64 v[4:5], v[6:7], 0, v[12:13]
	global_store_short_d16_hi v[4:5], v8, off sc1
	v_mul_f32_e32 v4, v147, v118
	v_mul_f32_e32 v4, v130, v4
	v_bfe_u32 v5, v4, 16, 1
	v_add3_u32 v8, v4, v5, s30
	v_lshl_add_u64 v[4:5], v[6:7], 0, v[14:15]
	global_store_short_d16_hi v[4:5], v8, off sc1
	v_mul_f32_e32 v4, v148, v120
	v_mul_f32_e32 v4, v130, v4
	v_bfe_u32 v5, v4, 16, 1
	v_add3_u32 v8, v4, v5, s30
	v_lshl_add_u64 v[4:5], v[6:7], 0, v[80:81]
	global_store_short_d16_hi v[4:5], v8, off sc1
	v_mul_f32_e32 v4, v150, v121
	v_mul_f32_e32 v4, v130, v4
	v_bfe_u32 v5, v4, 16, 1
	v_add3_u32 v8, v4, v5, s30
	v_lshl_add_u64 v[4:5], v[6:7], 0, v[82:83]
	global_store_short_d16_hi v[4:5], v8, off sc1
	v_mul_f32_e32 v4, v153, v123
	v_mul_f32_e32 v4, v130, v4
	v_bfe_u32 v5, v4, 16, 1
	v_add3_u32 v8, v4, v5, s30
	v_lshl_add_u64 v[4:5], v[6:7], 0, v[84:85]
	global_store_short_d16_hi v[4:5], v8, off sc1
	v_mul_f32_e32 v4, v156, v122
	v_mul_f32_e32 v4, v130, v4
	v_bfe_u32 v5, v4, 16, 1
	v_add3_u32 v8, v4, v5, s30
	v_lshl_add_u64 v[4:5], v[6:7], 0, v[86:87]
	global_store_short_d16_hi v[4:5], v8, off sc1
	v_mul_f32_e32 v4, v159, v124
	v_mul_f32_e32 v4, v130, v4
	v_bfe_u32 v5, v4, 16, 1
	v_add3_u32 v8, v4, v5, s30
	v_lshl_add_u64 v[4:5], v[6:7], 0, v[88:89]
	global_store_short_d16_hi v[4:5], v8, off sc1
	v_mul_f32_e32 v4, v160, v125
	v_mul_f32_e32 v4, v130, v4
	v_bfe_u32 v5, v4, 16, 1
	v_add3_u32 v8, v4, v5, s30
	v_lshl_add_u64 v[4:5], v[6:7], 0, v[90:91]
	global_store_short_d16_hi v[4:5], v8, off sc1
	v_mul_f32_e32 v4, v161, v127
	v_mul_f32_e32 v4, v130, v4
	v_bfe_u32 v5, v4, 16, 1
	v_add3_u32 v8, v4, v5, s30
	v_lshl_add_u64 v[4:5], v[6:7], 0, v[92:93]
	global_store_short_d16_hi v[4:5], v8, off sc1
	v_mul_f32_e32 v4, v162, v126
	v_mul_f32_e32 v4, v130, v4
	v_bfe_u32 v5, v4, 16, 1
	v_add3_u32 v8, v4, v5, s30
	v_lshl_add_u64 v[4:5], v[6:7], 0, v[94:95]
	global_store_short_d16_hi v[4:5], v8, off sc1
	v_mul_f32_e32 v4, v163, v128
	v_mul_f32_e32 v4, v130, v4
	v_bfe_u32 v5, v4, 16, 1
	v_add3_u32 v8, v4, v5, s30
	v_lshl_add_u64 v[4:5], v[6:7], 0, v[96:97]
	global_store_short_d16_hi v[4:5], v8, off sc1
	v_mul_f32_e32 v4, v165, v129
	v_mul_f32_e32 v4, v130, v4
	v_bfe_u32 v5, v4, 16, 1
	v_add3_u32 v8, v4, v5, s30
	v_lshl_add_u64 v[4:5], v[6:7], 0, v[2:3]
	global_store_short_d16_hi v[4:5], v8, off sc1
.LBB0_1479:
	s_andn2_b64 vcc, exec, s[4:5]
	s_cbranch_vccnz .LBB0_1405
	v_mul_f32_e32 v2, v113, v64
	global_store_dword v[0:1], v2, off sc1
	v_mul_f32_e32 v2, v112, v65
	v_add_co_u32_e32 v4, vcc, 0x1000, v0
	global_store_dword v[0:1], v2, off offset:2048 sc1
	v_mul_f32_e32 v2, v111, v66
	v_addc_co_u32_e32 v5, vcc, 0, v1, vcc
	global_store_dword v[4:5], v2, off sc1
	v_mul_f32_e32 v2, v110, v67
	s_movk_i32 s4, 0x2000
	global_store_dword v[4:5], v2, off offset:2048 sc1
	v_add_co_u32_e32 v4, vcc, s4, v0
	v_mul_f32_e32 v2, v109, v68
	s_nop 0
	v_addc_co_u32_e32 v5, vcc, 0, v1, vcc
	v_add_co_u32_e32 v6, vcc, s85, v0
	s_movk_i32 s4, 0x4000
	s_nop 0
	v_addc_co_u32_e32 v7, vcc, 0, v1, vcc
	global_store_dword v[6:7], v2, off offset:-4096 sc1
	v_mul_f32_e32 v2, v108, v69
	global_store_dword v[4:5], v2, off offset:2048 sc1
	v_mul_f32_e32 v2, v107, v70
	v_add_co_u32_e32 v4, vcc, s4, v0
	global_store_dword v[6:7], v2, off sc1
	v_mul_f32_e32 v2, v106, v71
	v_addc_co_u32_e32 v5, vcc, 0, v1, vcc
	global_store_dword v[6:7], v2, off offset:2048 sc1
	v_add_co_u32_e32 v6, vcc, s91, v0
	v_mul_f32_e32 v2, v105, v72
	s_nop 0
	v_addc_co_u32_e32 v7, vcc, 0, v1, vcc
	global_store_dword v[6:7], v2, off offset:-4096 sc1
	v_mul_f32_e32 v2, v104, v73
	s_movk_i32 s4, 0x6000
	global_store_dword v[4:5], v2, off offset:2048 sc1
	v_mul_f32_e32 v2, v103, v74
	v_add_co_u32_e32 v4, vcc, s4, v0
	global_store_dword v[6:7], v2, off sc1
	v_mul_f32_e32 v2, v102, v75
	v_addc_co_u32_e32 v5, vcc, 0, v1, vcc
	global_store_dword v[6:7], v2, off offset:2048 sc1
	v_add_co_u32_e32 v6, vcc, s97, v0
	v_mul_f32_e32 v2, v101, v76
	s_nop 0
	v_addc_co_u32_e32 v7, vcc, 0, v1, vcc
	global_store_dword v[6:7], v2, off offset:-4096 sc1
	v_mul_f32_e32 v2, v100, v77
	s_mov_b32 s4, 0x8000
	global_store_dword v[4:5], v2, off offset:2048 sc1
	v_mul_f32_e32 v2, v99, v78
	v_add_co_u32_e32 v4, vcc, s4, v0
	global_store_dword v[6:7], v2, off sc1
	v_mul_f32_e32 v2, v98, v79
	v_addc_co_u32_e32 v5, vcc, 0, v1, vcc
	global_store_dword v[6:7], v2, off offset:2048 sc1
	v_add_co_u32_e32 v6, vcc, s74, v0
	v_mul_f32_e32 v2, v113, v48
	s_nop 0
	v_addc_co_u32_e32 v7, vcc, 0, v1, vcc
	global_store_dword v[6:7], v2, off offset:-4096 sc1
	v_mul_f32_e32 v2, v112, v49
	global_store_dword v[4:5], v2, off offset:2048 sc1
	v_mul_f32_e32 v2, v111, v50
	v_add_co_u32_e32 v4, vcc, s75, v0
	global_store_dword v[6:7], v2, off sc1
	v_mul_f32_e32 v2, v110, v51
	v_addc_co_u32_e32 v5, vcc, 0, v1, vcc
	global_store_dword v[6:7], v2, off offset:2048 sc1
	v_add_co_u32_e32 v6, vcc, s84, v0
	v_mul_f32_e32 v2, v109, v52
	s_nop 0
	v_addc_co_u32_e32 v7, vcc, 0, v1, vcc
	global_store_dword v[6:7], v2, off offset:-4096 sc1
	v_mul_f32_e32 v2, v108, v53
	s_mov_b32 s4, 0xc000
	global_store_dword v[4:5], v2, off offset:2048 sc1
	v_mul_f32_e32 v2, v107, v54
	v_add_co_u32_e32 v4, vcc, s4, v0
	global_store_dword v[6:7], v2, off sc1
	v_mul_f32_e32 v2, v106, v55
	v_addc_co_u32_e32 v5, vcc, 0, v1, vcc
	global_store_dword v[6:7], v2, off offset:2048 sc1
	v_add_co_u32_e32 v6, vcc, s90, v0
	v_mul_f32_e32 v2, v105, v56
	s_nop 0
	v_addc_co_u32_e32 v7, vcc, 0, v1, vcc
	global_store_dword v[6:7], v2, off offset:-4096 sc1
	v_mul_f32_e32 v2, v104, v57
	global_store_dword v[4:5], v2, off offset:2048 sc1
	v_mul_f32_e32 v2, v103, v58
	v_add_co_u32_e32 v4, vcc, s92, v0
	global_store_dword v[6:7], v2, off sc1
	v_mul_f32_e32 v2, v102, v59
	v_addc_co_u32_e32 v5, vcc, 0, v1, vcc
	global_store_dword v[6:7], v2, off offset:2048 sc1
	v_add_co_u32_e32 v6, vcc, s96, v0
	v_mul_f32_e32 v2, v101, v60
	s_nop 0
	v_addc_co_u32_e32 v7, vcc, 0, v1, vcc
	global_store_dword v[6:7], v2, off offset:-4096 sc1
	v_mul_f32_e32 v2, v100, v61
	s_mov_b32 s4, 0x10000
	global_store_dword v[4:5], v2, off offset:2048 sc1
	v_mul_f32_e32 v2, v99, v62
	v_add_co_u32_e32 v4, vcc, s4, v0
	global_store_dword v[6:7], v2, off sc1
	v_mul_f32_e32 v2, v98, v63
	v_addc_co_u32_e32 v5, vcc, 0, v1, vcc
	global_store_dword v[6:7], v2, off offset:2048 sc1
	v_add_co_u32_e32 v6, vcc, s73, v0
	v_mul_f32_e32 v2, v113, v32
	s_nop 0
	v_addc_co_u32_e32 v7, vcc, 0, v1, vcc
	global_store_dword v[6:7], v2, off offset:-4096 sc1
	v_mul_f32_e32 v2, v112, v33
	global_store_dword v[4:5], v2, off offset:2048 sc1
	v_mul_f32_e32 v2, v111, v34
	v_add_co_u32_e32 v4, vcc, s76, v0
	global_store_dword v[6:7], v2, off sc1
	v_mul_f32_e32 v2, v110, v35
	v_addc_co_u32_e32 v5, vcc, 0, v1, vcc
	global_store_dword v[6:7], v2, off offset:2048 sc1
	v_add_co_u32_e32 v6, vcc, s79, v0
	v_mul_f32_e32 v2, v109, v36
	s_nop 0
	v_addc_co_u32_e32 v7, vcc, 0, v1, vcc
	global_store_dword v[6:7], v2, off offset:-4096 sc1
	v_mul_f32_e32 v2, v108, v37
	global_store_dword v[4:5], v2, off offset:2048 sc1
	v_mul_f32_e32 v2, v107, v38
	v_add_co_u32_e32 v4, vcc, s86, v0
	global_store_dword v[6:7], v2, off sc1
	v_mul_f32_e32 v2, v106, v39
	v_addc_co_u32_e32 v5, vcc, 0, v1, vcc
	global_store_dword v[6:7], v2, off offset:2048 sc1
	v_add_co_u32_e32 v6, vcc, s89, v0
	v_mul_f32_e32 v2, v105, v40
	s_nop 0
	v_addc_co_u32_e32 v7, vcc, 0, v1, vcc
	global_store_dword v[6:7], v2, off offset:-4096 sc1
	v_mul_f32_e32 v2, v104, v41
	global_store_dword v[4:5], v2, off offset:2048 sc1
	v_mul_f32_e32 v2, v103, v42
	v_add_co_u32_e32 v4, vcc, s93, v0
	global_store_dword v[6:7], v2, off sc1
	v_mul_f32_e32 v2, v102, v43
	v_addc_co_u32_e32 v5, vcc, 0, v1, vcc
	global_store_dword v[6:7], v2, off offset:2048 sc1
	v_add_co_u32_e32 v6, vcc, s95, v0
	v_mul_f32_e32 v2, v101, v44
	s_nop 0
	v_addc_co_u32_e32 v7, vcc, 0, v1, vcc
	global_store_dword v[6:7], v2, off offset:-4096 sc1
	v_mul_f32_e32 v2, v100, v45
	s_mov_b32 s4, 0x18000
	global_store_dword v[4:5], v2, off offset:2048 sc1
	v_mul_f32_e32 v2, v99, v46
	v_add_co_u32_e32 v4, vcc, s4, v0
	global_store_dword v[6:7], v2, off sc1
	v_mul_f32_e32 v2, v98, v47
	v_addc_co_u32_e32 v5, vcc, 0, v1, vcc
	global_store_dword v[6:7], v2, off offset:2048 sc1
	v_add_co_u32_e32 v6, vcc, s72, v0
	v_mul_f32_e32 v2, v113, v16
	s_nop 0
	v_addc_co_u32_e32 v7, vcc, 0, v1, vcc
	global_store_dword v[6:7], v2, off offset:-4096 sc1
	v_mul_f32_e32 v2, v112, v17
	global_store_dword v[4:5], v2, off offset:2048 sc1
	v_mul_f32_e32 v2, v111, v18
	v_add_co_u32_e32 v4, vcc, s77, v0
	global_store_dword v[6:7], v2, off sc1
	v_mul_f32_e32 v2, v110, v19
	v_addc_co_u32_e32 v5, vcc, 0, v1, vcc
	global_store_dword v[6:7], v2, off offset:2048 sc1
	v_add_co_u32_e32 v6, vcc, s78, v0
	v_mul_f32_e32 v2, v109, v20
	s_nop 0
	v_addc_co_u32_e32 v7, vcc, 0, v1, vcc
	global_store_dword v[6:7], v2, off offset:-4096 sc1
	v_mul_f32_e32 v2, v108, v21
	global_store_dword v[4:5], v2, off offset:2048 sc1
	v_mul_f32_e32 v2, v107, v22
	v_add_co_u32_e32 v4, vcc, s87, v0
	global_store_dword v[6:7], v2, off sc1
	v_mul_f32_e32 v2, v106, v23
	v_addc_co_u32_e32 v5, vcc, 0, v1, vcc
	global_store_dword v[6:7], v2, off offset:2048 sc1
	v_add_co_u32_e32 v6, vcc, s88, v0
	v_mul_f32_e32 v2, v105, v24
	s_nop 0
	v_addc_co_u32_e32 v7, vcc, 0, v1, vcc
	global_store_dword v[6:7], v2, off offset:-4096 sc1
	v_mul_f32_e32 v2, v104, v25
	global_store_dword v[4:5], v2, off offset:2048 sc1
	v_mul_f32_e32 v2, v103, v26
	global_store_dword v[6:7], v2, off sc1
	v_mul_f32_e32 v2, v102, v27
	v_add_co_u32_e32 v4, vcc, s94, v0
	global_store_dword v[6:7], v2, off offset:2048 sc1
	v_mul_f32_e32 v2, v101, v28
	v_addc_co_u32_e32 v5, vcc, 0, v1, vcc
	global_store_dword v[4:5], v2, off sc1
	v_mul_f32_e32 v2, v100, v29
	v_add_co_u32_e32 v0, vcc, 0x1f000, v0
	global_store_dword v[4:5], v2, off offset:2048 sc1
	v_mul_f32_e32 v2, v99, v30
	v_addc_co_u32_e32 v1, vcc, 0, v1, vcc
	global_store_dword v[0:1], v2, off sc1
	v_mul_f32_e32 v2, v98, v31
	global_store_dword v[0:1], v2, off offset:2048 sc1
	s_branch .LBB0_1405
